# speedup vs baseline: 1.0146x; 1.0146x over previous
.LBB0_364:
	ds_read_b128 v[138:141], v137
	ds_read_b128 v[142:145], v137 offset:1024
	ds_read_b128 v[146:149], v137 offset:2048
	ds_read_b128 v[150:153], v137 offset:3072
	s_add_u32 s64, s20, s18
	s_addc_u32 s65, s21, s19
	s_add_u32 s62, s64, 0x180
	s_addc_u32 s63, s65, 0
	s_mov_b32 m0, s42
	ds_read_b128 v[154:157], v136
	ds_read_b128 v[158:161], v136 offset:1024
	ds_read_b128 v[162:165], v136 offset:2048
	ds_read_b128 v[166:169], v136 offset:3072
	ds_read_b128 v[170:173], v136 offset:4096
	ds_read_b128 v[174:177], v136 offset:5120
	ds_read_b128 v[178:181], v136 offset:6144
	ds_read_b128 v[182:185], v136 offset:7168
	ds_read_b128 v[186:189], v137 offset:16384
	ds_read_b128 v[190:193], v137 offset:17408
	ds_read_b128 v[194:197], v137 offset:18432
	ds_read_b128 v[198:201], v137 offset:19456
	s_nop 0
	global_load_lds_dwordx4 v130, s[62:63]
	s_mov_b32 m0, s43
	s_nop 0
	global_load_lds_dwordx4 v132, s[62:63]
	s_waitcnt lgkmcnt(0)
	s_barrier
	s_setprio 3
	v_mfma_f32_16x16x32_bf16 v[30:33], v[154:157], v[138:141], v[30:33]
	v_mfma_f32_16x16x32_bf16 v[26:29], v[154:157], v[146:149], v[26:29]
	v_mfma_f32_16x16x32_bf16 v[22:25], v[162:165], v[138:141], v[22:25]
	v_mfma_f32_16x16x32_bf16 v[18:21], v[162:165], v[146:149], v[18:21]
	v_mfma_f32_16x16x32_bf16 v[14:17], v[170:173], v[138:141], v[14:17]
	v_mfma_f32_16x16x32_bf16 v[10:13], v[170:173], v[146:149], v[10:13]
	v_mfma_f32_16x16x32_bf16 v[6:9], v[178:181], v[138:141], v[6:9]
	v_mfma_f32_16x16x32_bf16 v[2:5], v[178:181], v[146:149], v[2:5]
	v_mfma_f32_16x16x32_bf16 v[30:33], v[158:161], v[142:145], v[30:33]
	v_mfma_f32_16x16x32_bf16 v[26:29], v[158:161], v[150:153], v[26:29]
	v_mfma_f32_16x16x32_bf16 v[22:25], v[166:169], v[142:145], v[22:25]
	v_mfma_f32_16x16x32_bf16 v[18:21], v[166:169], v[150:153], v[18:21]
	v_mfma_f32_16x16x32_bf16 v[14:17], v[174:177], v[142:145], v[14:17]
	v_mfma_f32_16x16x32_bf16 v[10:13], v[174:177], v[150:153], v[10:13]
	v_mfma_f32_16x16x32_bf16 v[6:9], v[182:185], v[142:145], v[6:9]
	v_mfma_f32_16x16x32_bf16 v[2:5], v[182:185], v[150:153], v[2:5]
	v_mfma_f32_16x16x32_bf16 v[62:65], v[154:157], v[186:189], v[62:65]
	v_mfma_f32_16x16x32_bf16 v[58:61], v[154:157], v[194:197], v[58:61]
	v_mfma_f32_16x16x32_bf16 v[54:57], v[162:165], v[186:189], v[54:57]
	v_mfma_f32_16x16x32_bf16 v[50:53], v[162:165], v[194:197], v[50:53]
	v_mfma_f32_16x16x32_bf16 v[46:49], v[170:173], v[186:189], v[46:49]
	v_mfma_f32_16x16x32_bf16 v[42:45], v[170:173], v[194:197], v[42:45]
	v_mfma_f32_16x16x32_bf16 v[38:41], v[178:181], v[186:189], v[38:41]
	v_mfma_f32_16x16x32_bf16 v[34:37], v[178:181], v[194:197], v[34:37]
	v_mfma_f32_16x16x32_bf16 v[62:65], v[158:161], v[190:193], v[62:65]
	v_mfma_f32_16x16x32_bf16 v[58:61], v[158:161], v[198:201], v[58:61]
	v_mfma_f32_16x16x32_bf16 v[54:57], v[166:169], v[190:193], v[54:57]
	v_mfma_f32_16x16x32_bf16 v[50:53], v[166:169], v[198:201], v[50:53]
	v_mfma_f32_16x16x32_bf16 v[46:49], v[174:177], v[190:193], v[46:49]
	v_mfma_f32_16x16x32_bf16 v[42:45], v[174:177], v[198:201], v[42:45]
	v_mfma_f32_16x16x32_bf16 v[38:41], v[182:185], v[190:193], v[38:41]
	v_mfma_f32_16x16x32_bf16 v[34:37], v[182:185], v[198:201], v[34:37]
	s_setprio 0
	s_barrier
	ds_read_b128 v[154:157], v136 offset:16384
	ds_read_b128 v[158:161], v136 offset:17408
	ds_read_b128 v[162:165], v136 offset:18432
	ds_read_b128 v[166:169], v136 offset:19456
	ds_read_b128 v[170:173], v136 offset:20480
	ds_read_b128 v[174:177], v136 offset:21504
	ds_read_b128 v[178:181], v136 offset:22528
	ds_read_b128 v[182:185], v136 offset:23552
	s_add_u32 s66, s56, s18
	s_addc_u32 s67, s57, s19
	s_add_u32 s62, s66, 0x200
	s_addc_u32 s63, s67, 0
	s_mov_b32 m0, s28
	s_nop 0
	global_load_lds_dwordx4 v130, s[62:63]
	s_mov_b32 m0, s29
	s_nop 0
	global_load_lds_dwordx4 v132, s[62:63]
	s_add_u32 s68, s17, s18
	s_addc_u32 s69, s58, s19
	s_add_u32 s62, s68, 0x200
	s_addc_u32 s63, s69, 0
	s_mov_b32 m0, s27
	s_nop 0
	global_load_lds_dwordx4 v130, s[62:63]
	s_mov_b32 m0, s30
	s_nop 0
	global_load_lds_dwordx4 v132, s[62:63]
	s_add_u32 s70, s59, s18
	s_addc_u32 s71, s60, s19
	s_add_u32 s62, s70, 0x200
	s_addc_u32 s63, s71, 0
	s_mov_b32 m0, s31
	s_nop 0
	global_load_lds_dwordx4 v130, s[62:63]
	s_mov_b32 m0, s33
	s_nop 0
	global_load_lds_dwordx4 v132, s[62:63]
	s_waitcnt vmcnt(6)
	s_waitcnt lgkmcnt(0)
	s_barrier
	s_setprio 3
	v_mfma_f32_16x16x32_bf16 v[94:97], v[154:157], v[138:141], v[94:97]
	v_mfma_f32_16x16x32_bf16 v[90:93], v[154:157], v[146:149], v[90:93]
	v_mfma_f32_16x16x32_bf16 v[86:89], v[162:165], v[138:141], v[86:89]
	v_mfma_f32_16x16x32_bf16 v[82:85], v[162:165], v[146:149], v[82:85]
	v_mfma_f32_16x16x32_bf16 v[78:81], v[170:173], v[138:141], v[78:81]
	v_mfma_f32_16x16x32_bf16 v[74:77], v[170:173], v[146:149], v[74:77]
	v_mfma_f32_16x16x32_bf16 v[70:73], v[178:181], v[138:141], v[70:73]
	v_mfma_f32_16x16x32_bf16 v[66:69], v[178:181], v[146:149], v[66:69]
	v_mfma_f32_16x16x32_bf16 v[94:97], v[158:161], v[142:145], v[94:97]
	v_mfma_f32_16x16x32_bf16 v[90:93], v[158:161], v[150:153], v[90:93]
	v_mfma_f32_16x16x32_bf16 v[86:89], v[166:169], v[142:145], v[86:89]
	v_mfma_f32_16x16x32_bf16 v[82:85], v[166:169], v[150:153], v[82:85]
	v_mfma_f32_16x16x32_bf16 v[78:81], v[174:177], v[142:145], v[78:81]
	v_mfma_f32_16x16x32_bf16 v[74:77], v[174:177], v[150:153], v[74:77]
	v_mfma_f32_16x16x32_bf16 v[70:73], v[182:185], v[142:145], v[70:73]
	v_mfma_f32_16x16x32_bf16 v[66:69], v[182:185], v[150:153], v[66:69]
	v_mfma_f32_16x16x32_bf16 v[126:129], v[154:157], v[186:189], v[126:129]
	v_mfma_f32_16x16x32_bf16 v[122:125], v[154:157], v[194:197], v[122:125]
	v_mfma_f32_16x16x32_bf16 v[118:121], v[162:165], v[186:189], v[118:121]
	v_mfma_f32_16x16x32_bf16 v[114:117], v[162:165], v[194:197], v[114:117]
	v_mfma_f32_16x16x32_bf16 v[110:113], v[170:173], v[186:189], v[110:113]
	v_mfma_f32_16x16x32_bf16 v[106:109], v[170:173], v[194:197], v[106:109]
	v_mfma_f32_16x16x32_bf16 v[102:105], v[178:181], v[186:189], v[102:105]
	v_mfma_f32_16x16x32_bf16 v[98:101], v[178:181], v[194:197], v[98:101]
	v_mfma_f32_16x16x32_bf16 v[126:129], v[158:161], v[190:193], v[126:129]
	v_mfma_f32_16x16x32_bf16 v[122:125], v[158:161], v[198:201], v[122:125]
	v_mfma_f32_16x16x32_bf16 v[118:121], v[166:169], v[190:193], v[118:121]
	v_mfma_f32_16x16x32_bf16 v[114:117], v[166:169], v[198:201], v[114:117]
	v_mfma_f32_16x16x32_bf16 v[110:113], v[174:177], v[190:193], v[110:113]
	v_mfma_f32_16x16x32_bf16 v[106:109], v[174:177], v[198:201], v[106:109]
	v_mfma_f32_16x16x32_bf16 v[102:105], v[182:185], v[190:193], v[102:105]
	v_mfma_f32_16x16x32_bf16 v[98:101], v[182:185], v[198:201], v[98:101]
	s_setprio 0
	s_barrier
	ds_read_b128 v[138:141], v137 offset:32768
	ds_read_b128 v[142:145], v137 offset:33792
	ds_read_b128 v[146:149], v137 offset:34816
	ds_read_b128 v[150:153], v137 offset:35840
	s_add_u32 s62, s64, 0x200
	s_addc_u32 s63, s65, 0
	s_mov_b32 m0, s34
	ds_read_b128 v[154:157], v136 offset:32768
	ds_read_b128 v[158:161], v136 offset:33792
	ds_read_b128 v[162:165], v136 offset:34816
	ds_read_b128 v[166:169], v136 offset:35840
	ds_read_b128 v[170:173], v136 offset:36864
	ds_read_b128 v[174:177], v136 offset:37888
	ds_read_b128 v[178:181], v136 offset:38912
	ds_read_b128 v[182:185], v136 offset:39936
	ds_read_b128 v[186:189], v137 offset:49152
	ds_read_b128 v[190:193], v137 offset:50176
	ds_read_b128 v[194:197], v137 offset:51200
	ds_read_b128 v[198:201], v137 offset:52224
	s_nop 0
	global_load_lds_dwordx4 v130, s[62:63]
	s_mov_b32 m0, s35
	s_nop 0
	global_load_lds_dwordx4 v132, s[62:63]
	s_waitcnt lgkmcnt(0)
	s_barrier
	s_setprio 3
	v_mfma_f32_16x16x32_bf16 v[30:33], v[154:157], v[138:141], v[30:33]
	v_mfma_f32_16x16x32_bf16 v[26:29], v[154:157], v[146:149], v[26:29]
	v_mfma_f32_16x16x32_bf16 v[22:25], v[162:165], v[138:141], v[22:25]
	v_mfma_f32_16x16x32_bf16 v[18:21], v[162:165], v[146:149], v[18:21]
	v_mfma_f32_16x16x32_bf16 v[14:17], v[170:173], v[138:141], v[14:17]
	v_mfma_f32_16x16x32_bf16 v[10:13], v[170:173], v[146:149], v[10:13]
	v_mfma_f32_16x16x32_bf16 v[6:9], v[178:181], v[138:141], v[6:9]
	v_mfma_f32_16x16x32_bf16 v[2:5], v[178:181], v[146:149], v[2:5]
	v_mfma_f32_16x16x32_bf16 v[30:33], v[158:161], v[142:145], v[30:33]
	v_mfma_f32_16x16x32_bf16 v[26:29], v[158:161], v[150:153], v[26:29]
	v_mfma_f32_16x16x32_bf16 v[22:25], v[166:169], v[142:145], v[22:25]
	v_mfma_f32_16x16x32_bf16 v[18:21], v[166:169], v[150:153], v[18:21]
	v_mfma_f32_16x16x32_bf16 v[14:17], v[174:177], v[142:145], v[14:17]
	v_mfma_f32_16x16x32_bf16 v[10:13], v[174:177], v[150:153], v[10:13]
	v_mfma_f32_16x16x32_bf16 v[6:9], v[182:185], v[142:145], v[6:9]
	v_mfma_f32_16x16x32_bf16 v[2:5], v[182:185], v[150:153], v[2:5]
	v_mfma_f32_16x16x32_bf16 v[62:65], v[154:157], v[186:189], v[62:65]
	v_mfma_f32_16x16x32_bf16 v[58:61], v[154:157], v[194:197], v[58:61]
	v_mfma_f32_16x16x32_bf16 v[54:57], v[162:165], v[186:189], v[54:57]
	v_mfma_f32_16x16x32_bf16 v[50:53], v[162:165], v[194:197], v[50:53]
	v_mfma_f32_16x16x32_bf16 v[46:49], v[170:173], v[186:189], v[46:49]
	v_mfma_f32_16x16x32_bf16 v[42:45], v[170:173], v[194:197], v[42:45]
	v_mfma_f32_16x16x32_bf16 v[38:41], v[178:181], v[186:189], v[38:41]
	v_mfma_f32_16x16x32_bf16 v[34:37], v[178:181], v[194:197], v[34:37]
	v_mfma_f32_16x16x32_bf16 v[62:65], v[158:161], v[190:193], v[62:65]
	v_mfma_f32_16x16x32_bf16 v[58:61], v[158:161], v[198:201], v[58:61]
	v_mfma_f32_16x16x32_bf16 v[54:57], v[166:169], v[190:193], v[54:57]
	v_mfma_f32_16x16x32_bf16 v[50:53], v[166:169], v[198:201], v[50:53]
	v_mfma_f32_16x16x32_bf16 v[46:49], v[174:177], v[190:193], v[46:49]
	v_mfma_f32_16x16x32_bf16 v[42:45], v[174:177], v[198:201], v[42:45]
	v_mfma_f32_16x16x32_bf16 v[38:41], v[182:185], v[190:193], v[38:41]
	v_mfma_f32_16x16x32_bf16 v[34:37], v[182:185], v[198:201], v[34:37]
	s_setprio 0
	s_barrier
	ds_read_b128 v[154:157], v136 offset:49152
	ds_read_b128 v[158:161], v136 offset:50176
	ds_read_b128 v[162:165], v136 offset:51200
	ds_read_b128 v[166:169], v136 offset:52224
	ds_read_b128 v[170:173], v136 offset:53248
	ds_read_b128 v[174:177], v136 offset:54272
	ds_read_b128 v[178:181], v136 offset:55296
	ds_read_b128 v[182:185], v136 offset:56320
	s_add_u32 s62, s66, 0x280
	s_addc_u32 s63, s67, 0
	s_mov_b32 m0, s36
	s_nop 0
	global_load_lds_dwordx4 v130, s[62:63]
	s_mov_b32 m0, s37
	s_nop 0
	global_load_lds_dwordx4 v132, s[62:63]
	s_add_u32 s62, s68, 0x280
	s_addc_u32 s63, s69, 0
	s_mov_b32 m0, s38
	s_nop 0
	global_load_lds_dwordx4 v130, s[62:63]
	s_mov_b32 m0, s39
	s_nop 0
	global_load_lds_dwordx4 v132, s[62:63]
	s_add_u32 s62, s70, 0x280
	s_addc_u32 s63, s71, 0
	s_mov_b32 m0, s40
	s_nop 0
	global_load_lds_dwordx4 v130, s[62:63]
	s_mov_b32 m0, s41
	s_nop 0
	global_load_lds_dwordx4 v132, s[62:63]
	s_waitcnt vmcnt(6)
	s_waitcnt lgkmcnt(0)
	s_barrier
	s_setprio 3
	v_mfma_f32_16x16x32_bf16 v[94:97], v[154:157], v[138:141], v[94:97]
	v_mfma_f32_16x16x32_bf16 v[90:93], v[154:157], v[146:149], v[90:93]
	v_mfma_f32_16x16x32_bf16 v[86:89], v[162:165], v[138:141], v[86:89]
	v_mfma_f32_16x16x32_bf16 v[82:85], v[162:165], v[146:149], v[82:85]
	v_mfma_f32_16x16x32_bf16 v[78:81], v[170:173], v[138:141], v[78:81]
	v_mfma_f32_16x16x32_bf16 v[74:77], v[170:173], v[146:149], v[74:77]
	v_mfma_f32_16x16x32_bf16 v[70:73], v[178:181], v[138:141], v[70:73]
	v_mfma_f32_16x16x32_bf16 v[66:69], v[178:181], v[146:149], v[66:69]
	v_mfma_f32_16x16x32_bf16 v[94:97], v[158:161], v[142:145], v[94:97]
	v_mfma_f32_16x16x32_bf16 v[90:93], v[158:161], v[150:153], v[90:93]
	v_mfma_f32_16x16x32_bf16 v[86:89], v[166:169], v[142:145], v[86:89]
	v_mfma_f32_16x16x32_bf16 v[82:85], v[166:169], v[150:153], v[82:85]
	v_mfma_f32_16x16x32_bf16 v[78:81], v[174:177], v[142:145], v[78:81]
	v_mfma_f32_16x16x32_bf16 v[74:77], v[174:177], v[150:153], v[74:77]
	v_mfma_f32_16x16x32_bf16 v[70:73], v[182:185], v[142:145], v[70:73]
	v_mfma_f32_16x16x32_bf16 v[66:69], v[182:185], v[150:153], v[66:69]
	v_mfma_f32_16x16x32_bf16 v[126:129], v[154:157], v[186:189], v[126:129]
	v_mfma_f32_16x16x32_bf16 v[122:125], v[154:157], v[194:197], v[122:125]
	v_mfma_f32_16x16x32_bf16 v[118:121], v[162:165], v[186:189], v[118:121]
	v_mfma_f32_16x16x32_bf16 v[114:117], v[162:165], v[194:197], v[114:117]
	v_mfma_f32_16x16x32_bf16 v[110:113], v[170:173], v[186:189], v[110:113]
	v_mfma_f32_16x16x32_bf16 v[106:109], v[170:173], v[194:197], v[106:109]
	v_mfma_f32_16x16x32_bf16 v[102:105], v[178:181], v[186:189], v[102:105]
	v_mfma_f32_16x16x32_bf16 v[98:101], v[178:181], v[194:197], v[98:101]
	v_mfma_f32_16x16x32_bf16 v[126:129], v[158:161], v[190:193], v[126:129]
	v_mfma_f32_16x16x32_bf16 v[122:125], v[158:161], v[198:201], v[122:125]
	v_mfma_f32_16x16x32_bf16 v[118:121], v[166:169], v[190:193], v[118:121]
	v_mfma_f32_16x16x32_bf16 v[114:117], v[166:169], v[198:201], v[114:117]
	v_mfma_f32_16x16x32_bf16 v[110:113], v[174:177], v[190:193], v[110:113]
	v_mfma_f32_16x16x32_bf16 v[106:109], v[174:177], v[198:201], v[106:109]
	v_mfma_f32_16x16x32_bf16 v[102:105], v[182:185], v[190:193], v[102:105]
	v_mfma_f32_16x16x32_bf16 v[98:101], v[182:185], v[198:201], v[98:101]
	s_setprio 0
	s_add_i32 s61, s61, 2
	s_add_u32 s18, s18, 0x100
	s_addc_u32 s19, s19, 0
	s_cmp_gt_u32 s61, 11
	s_barrier
	s_cbranch_scc0 .LBB0_364
	s_lshl_b64 s[14:15], s[14:15], 1
	s_add_u32 s14, s44, s14
	s_addc_u32 s15, s45, s15
	s_mov_b32 m0, s42
	ds_read_b128 v[142:145], v137
	ds_read_b128 v[146:149], v137 offset:1024
	ds_read_b128 v[150:153], v137 offset:2048
	ds_read_b128 v[154:157], v137 offset:3072
	ds_read_b128 v[158:161], v136
	ds_read_b128 v[162:165], v136 offset:1024
	ds_read_b128 v[166:169], v136 offset:2048
	ds_read_b128 v[170:173], v136 offset:3072
	ds_read_b128 v[174:177], v136 offset:4096
	ds_read_b128 v[178:181], v136 offset:5120
	ds_read_b128 v[182:185], v136 offset:6144
	ds_read_b128 v[186:189], v136 offset:7168
	s_nop 0
	global_load_lds_dwordx4 v130, s[14:15]
	s_mov_b32 m0, s43
	s_nop 0
	global_load_lds_dwordx4 v132, s[14:15]
	s_barrier
	s_waitcnt lgkmcnt(0)
	s_setprio 3
	s_waitcnt lgkmcnt(0)
	v_mfma_f32_16x16x32_bf16 v[30:33], v[158:161], v[142:145], v[30:33]
	v_mfma_f32_16x16x32_bf16 v[26:29], v[158:161], v[150:153], v[26:29]
	v_mfma_f32_16x16x32_bf16 v[22:25], v[166:169], v[142:145], v[22:25]
	v_mfma_f32_16x16x32_bf16 v[18:21], v[166:169], v[150:153], v[18:21]
	v_mfma_f32_16x16x32_bf16 v[14:17], v[174:177], v[142:145], v[14:17]
	v_mfma_f32_16x16x32_bf16 v[10:13], v[174:177], v[150:153], v[10:13]
	v_mfma_f32_16x16x32_bf16 v[6:9], v[182:185], v[142:145], v[6:9]
	v_mfma_f32_16x16x32_bf16 v[2:5], v[182:185], v[150:153], v[2:5]
	v_mfma_f32_16x16x32_bf16 v[30:33], v[162:165], v[146:149], v[30:33]
	v_mfma_f32_16x16x32_bf16 v[26:29], v[162:165], v[154:157], v[26:29]
	v_mfma_f32_16x16x32_bf16 v[22:25], v[170:173], v[146:149], v[22:25]
	v_mfma_f32_16x16x32_bf16 v[18:21], v[170:173], v[154:157], v[18:21]
	v_mfma_f32_16x16x32_bf16 v[14:17], v[178:181], v[146:149], v[14:17]
	v_mfma_f32_16x16x32_bf16 v[10:13], v[178:181], v[154:157], v[10:13]
	v_mfma_f32_16x16x32_bf16 v[6:9], v[186:189], v[146:149], v[6:9]
	v_mfma_f32_16x16x32_bf16 v[2:5], v[186:189], v[154:157], v[2:5]
	s_setprio 0
	s_barrier
	ds_read_b128 v[190:193], v137 offset:16384
	ds_read_b128 v[194:197], v137 offset:17408
	ds_read_b128 v[198:201], v137 offset:18432
	ds_read_b128 v[202:205], v137 offset:19456
	s_barrier
	s_waitcnt lgkmcnt(0)
	s_setprio 3
	s_waitcnt lgkmcnt(0)
	v_mfma_f32_16x16x32_bf16 v[62:65], v[158:161], v[190:193], v[62:65]
	v_mfma_f32_16x16x32_bf16 v[58:61], v[158:161], v[198:201], v[58:61]
	v_mfma_f32_16x16x32_bf16 v[54:57], v[166:169], v[190:193], v[54:57]
	v_mfma_f32_16x16x32_bf16 v[50:53], v[166:169], v[198:201], v[50:53]
	v_mfma_f32_16x16x32_bf16 v[46:49], v[174:177], v[190:193], v[46:49]
	v_mfma_f32_16x16x32_bf16 v[42:45], v[174:177], v[198:201], v[42:45]
	v_mfma_f32_16x16x32_bf16 v[38:41], v[182:185], v[190:193], v[38:41]
	v_mfma_f32_16x16x32_bf16 v[34:37], v[182:185], v[198:201], v[34:37]
	v_mfma_f32_16x16x32_bf16 v[62:65], v[162:165], v[194:197], v[62:65]
	v_mfma_f32_16x16x32_bf16 v[58:61], v[162:165], v[202:205], v[58:61]
	v_mfma_f32_16x16x32_bf16 v[54:57], v[170:173], v[194:197], v[54:57]
	v_mfma_f32_16x16x32_bf16 v[50:53], v[170:173], v[202:205], v[50:53]
	v_mfma_f32_16x16x32_bf16 v[46:49], v[178:181], v[194:197], v[46:49]
	v_mfma_f32_16x16x32_bf16 v[42:45], v[178:181], v[202:205], v[42:45]
	v_mfma_f32_16x16x32_bf16 v[38:41], v[186:189], v[194:197], v[38:41]
	v_mfma_f32_16x16x32_bf16 v[34:37], v[186:189], v[202:205], v[34:37]
	s_setprio 0
	s_barrier
	ds_read_b128 v[158:161], v136 offset:16384
	ds_read_b128 v[162:165], v136 offset:17408
	ds_read_b128 v[166:169], v136 offset:18432
	ds_read_b128 v[170:173], v136 offset:19456
	ds_read_b128 v[174:177], v136 offset:20480
	ds_read_b128 v[178:181], v136 offset:21504
	ds_read_b128 v[182:185], v136 offset:22528
	ds_read_b128 v[186:189], v136 offset:23552
	s_waitcnt vmcnt(4)
	s_barrier
	s_waitcnt lgkmcnt(0)
	s_setprio 3
	s_waitcnt lgkmcnt(0)
	v_mfma_f32_16x16x32_bf16 v[94:97], v[158:161], v[142:145], v[94:97]
	v_mfma_f32_16x16x32_bf16 v[90:93], v[158:161], v[150:153], v[90:93]
	v_mfma_f32_16x16x32_bf16 v[86:89], v[166:169], v[142:145], v[86:89]
	v_mfma_f32_16x16x32_bf16 v[82:85], v[166:169], v[150:153], v[82:85]
	v_mfma_f32_16x16x32_bf16 v[78:81], v[174:177], v[142:145], v[78:81]
	v_mfma_f32_16x16x32_bf16 v[74:77], v[174:177], v[150:153], v[74:77]
	v_mfma_f32_16x16x32_bf16 v[70:73], v[182:185], v[142:145], v[70:73]
	v_mfma_f32_16x16x32_bf16 v[66:69], v[182:185], v[150:153], v[66:69]
	v_mfma_f32_16x16x32_bf16 v[212:215], v[162:165], v[146:149], v[94:97]
	v_mfma_f32_16x16x32_bf16 v[216:219], v[162:165], v[154:157], v[90:93]
	v_mfma_f32_16x16x32_bf16 v[220:223], v[170:173], v[146:149], v[86:89]
	v_mfma_f32_16x16x32_bf16 v[224:227], v[170:173], v[154:157], v[82:85]
	v_mfma_f32_16x16x32_bf16 v[228:231], v[178:181], v[146:149], v[78:81]
	v_mfma_f32_16x16x32_bf16 v[232:235], v[178:181], v[154:157], v[74:77]
	v_mfma_f32_16x16x32_bf16 v[142:145], v[186:189], v[146:149], v[70:73]
	v_mfma_f32_16x16x32_bf16 v[146:149], v[186:189], v[154:157], v[66:69]
	s_setprio 0
	s_setprio 3
	v_mfma_f32_16x16x32_bf16 v[66:69], v[158:161], v[190:193], v[126:129]
	v_mfma_f32_16x16x32_bf16 v[150:153], v[162:165], v[194:197], v[66:69]
	v_mfma_f32_16x16x32_bf16 v[66:69], v[158:161], v[198:201], v[122:125]
	v_mfma_f32_16x16x32_bf16 v[154:157], v[162:165], v[202:205], v[66:69]
	v_mfma_f32_16x16x32_bf16 v[66:69], v[166:169], v[190:193], v[118:121]
	v_mfma_f32_16x16x32_bf16 v[158:161], v[170:173], v[194:197], v[66:69]
	v_mfma_f32_16x16x32_bf16 v[66:69], v[166:169], v[198:201], v[114:117]
	v_mfma_f32_16x16x32_bf16 v[162:165], v[170:173], v[202:205], v[66:69]
	v_mfma_f32_16x16x32_bf16 v[66:69], v[174:177], v[190:193], v[110:113]
	v_mfma_f32_16x16x32_bf16 v[166:169], v[178:181], v[194:197], v[66:69]
	v_mfma_f32_16x16x32_bf16 v[66:69], v[174:177], v[198:201], v[106:109]
	v_mfma_f32_16x16x32_bf16 v[170:173], v[178:181], v[202:205], v[66:69]
	v_mfma_f32_16x16x32_bf16 v[66:69], v[182:185], v[190:193], v[102:105]
	v_mfma_f32_16x16x32_bf16 v[174:177], v[186:189], v[194:197], v[66:69]
	v_mfma_f32_16x16x32_bf16 v[66:69], v[182:185], v[198:201], v[98:101]
	v_mfma_f32_16x16x32_bf16 v[178:181], v[186:189], v[202:205], v[66:69]
	s_setprio 0
	s_barrier
	ds_read_b128 v[182:185], v137 offset:32768
	ds_read_b128 v[186:189], v137 offset:33792
	ds_read_b128 v[190:193], v137 offset:34816
	ds_read_b128 v[194:197], v137 offset:35840
	s_nop 0
	ds_read_b128 v[66:69], v136 offset:32768
	ds_read_b128 v[70:73], v136 offset:33792
	ds_read_b128 v[82:85], v136 offset:34816
	ds_read_b128 v[86:89], v136 offset:35840
	ds_read_b128 v[198:201], v136 offset:36864
	ds_read_b128 v[202:205], v136 offset:37888
	ds_read_b128 v[236:239], v136 offset:38912
	ds_read_b128 v[240:243], v136 offset:39936
	s_waitcnt vmcnt(2)
	s_barrier
	s_waitcnt lgkmcnt(0)
	s_setprio 3
	s_waitcnt lgkmcnt(0)
	v_mfma_f32_16x16x32_bf16 v[30:33], v[66:69], v[182:185], v[30:33]
	v_mfma_f32_16x16x32_bf16 v[26:29], v[66:69], v[190:193], v[26:29]
	v_mfma_f32_16x16x32_bf16 v[22:25], v[82:85], v[182:185], v[22:25]
	v_mfma_f32_16x16x32_bf16 v[18:21], v[82:85], v[190:193], v[18:21]
	v_mfma_f32_16x16x32_bf16 v[14:17], v[198:201], v[182:185], v[14:17]
	v_mfma_f32_16x16x32_bf16 v[10:13], v[198:201], v[190:193], v[10:13]
	v_mfma_f32_16x16x32_bf16 v[6:9], v[236:239], v[182:185], v[6:9]
	v_mfma_f32_16x16x32_bf16 v[2:5], v[236:239], v[190:193], v[2:5]
	v_mfma_f32_16x16x32_bf16 v[122:125], v[70:73], v[186:189], v[30:33]
	v_mfma_f32_16x16x32_bf16 v[126:129], v[70:73], v[194:197], v[26:29]
	v_mfma_f32_16x16x32_bf16 v[106:109], v[86:89], v[186:189], v[22:25]
	v_mfma_f32_16x16x32_bf16 v[110:113], v[86:89], v[194:197], v[18:21]
	v_mfma_f32_16x16x32_bf16 v[90:93], v[202:205], v[186:189], v[14:17]
	v_mfma_f32_16x16x32_bf16 v[94:97], v[202:205], v[194:197], v[10:13]
	v_mfma_f32_16x16x32_bf16 v[74:77], v[240:243], v[186:189], v[6:9]
	v_mfma_f32_16x16x32_bf16 v[78:81], v[240:243], v[194:197], v[2:5]
	s_setprio 0
	s_barrier
	s_nop 0
	ds_read_b128 v[2:5], v137 offset:49152
	ds_read_b128 v[6:9], v137 offset:50176
	ds_read_b128 v[244:247], v137 offset:51200
	ds_read_b128 v[248:251], v137 offset:52224
	s_waitcnt vmcnt(0)
	s_barrier
	s_waitcnt lgkmcnt(0)
	s_setprio 3
	s_waitcnt lgkmcnt(0)
	v_mfma_f32_16x16x32_bf16 v[10:13], v[66:69], v[2:5], v[62:65]
	v_mfma_f32_16x16x32_bf16 v[114:117], v[70:73], v[6:9], v[10:13]
	v_mfma_f32_16x16x32_bf16 v[10:13], v[66:69], v[244:247], v[58:61]
	v_mfma_f32_16x16x32_bf16 v[118:121], v[70:73], v[248:251], v[10:13]
	v_mfma_f32_16x16x32_bf16 v[10:13], v[82:85], v[2:5], v[54:57]
	v_mfma_f32_16x16x32_bf16 v[98:101], v[86:89], v[6:9], v[10:13]
	v_mfma_f32_16x16x32_bf16 v[10:13], v[82:85], v[244:247], v[50:53]
	v_mfma_f32_16x16x32_bf16 v[102:105], v[86:89], v[248:251], v[10:13]
	v_mfma_f32_16x16x32_bf16 v[10:13], v[198:201], v[2:5], v[46:49]
	v_mfma_f32_16x16x32_bf16 v[82:85], v[202:205], v[6:9], v[10:13]
	v_mfma_f32_16x16x32_bf16 v[10:13], v[198:201], v[244:247], v[42:45]
	v_mfma_f32_16x16x32_bf16 v[86:89], v[202:205], v[248:251], v[10:13]
	v_mfma_f32_16x16x32_bf16 v[10:13], v[236:239], v[2:5], v[38:41]
	v_mfma_f32_16x16x32_bf16 v[66:69], v[240:243], v[6:9], v[10:13]
	v_mfma_f32_16x16x32_bf16 v[10:13], v[236:239], v[244:247], v[34:37]
	v_mfma_f32_16x16x32_bf16 v[70:73], v[240:243], v[248:251], v[10:13]
	s_setprio 0
	s_barrier
	ds_read_b128 v[18:21], v136 offset:49152
	ds_read_b128 v[22:25], v136 offset:50176
	ds_read_b128 v[38:41], v136 offset:51200
	ds_read_b128 v[198:201], v136 offset:52224
	ds_read_b128 v[202:205], v136 offset:53248
	ds_read_b128 v[236:239], v136 offset:54272
	ds_read_b128 v[240:243], v136 offset:55296
	ds_read_b128 v[138:141], v136 offset:56320
	s_barrier
	s_waitcnt lgkmcnt(0)
	s_setprio 3
	s_waitcnt lgkmcnt(0)
	v_mfma_f32_16x16x32_bf16 v[10:13], v[18:21], v[182:185], v[212:215]
	v_mfma_f32_16x16x32_bf16 v[58:61], v[22:25], v[186:189], v[10:13]
	v_mfma_f32_16x16x32_bf16 v[10:13], v[18:21], v[190:193], v[216:219]
	v_mfma_f32_16x16x32_bf16 v[62:65], v[22:25], v[194:197], v[10:13]
	v_mfma_f32_16x16x32_bf16 v[10:13], v[38:41], v[182:185], v[220:223]
	v_mfma_f32_16x16x32_bf16 v[42:45], v[198:201], v[186:189], v[10:13]
	v_mfma_f32_16x16x32_bf16 v[10:13], v[38:41], v[190:193], v[224:227]
	v_mfma_f32_16x16x32_bf16 v[46:49], v[198:201], v[194:197], v[10:13]
	v_mfma_f32_16x16x32_bf16 v[10:13], v[202:205], v[182:185], v[228:231]
	v_mfma_f32_16x16x32_bf16 v[26:29], v[236:239], v[186:189], v[10:13]
	v_mfma_f32_16x16x32_bf16 v[10:13], v[202:205], v[190:193], v[232:235]
	v_mfma_f32_16x16x32_bf16 v[30:33], v[236:239], v[194:197], v[10:13]
	v_mfma_f32_16x16x32_bf16 v[10:13], v[240:243], v[182:185], v[142:145]
	v_mfma_f32_16x16x32_bf16 v[14:17], v[240:243], v[190:193], v[146:149]
	v_mfma_f32_16x16x32_bf16 v[10:13], v[138:141], v[186:189], v[10:13]
	v_mfma_f32_16x16x32_bf16 v[14:17], v[138:141], v[194:197], v[14:17]
	s_setprio 0
	s_setprio 3
	v_mfma_f32_16x16x32_bf16 v[34:37], v[18:21], v[2:5], v[150:153]
	v_mfma_f32_16x16x32_bf16 v[18:21], v[18:21], v[244:247], v[154:157]
	v_mfma_f32_16x16x32_bf16 v[54:57], v[22:25], v[248:251], v[18:21]
	v_mfma_f32_16x16x32_bf16 v[18:21], v[38:41], v[2:5], v[158:161]
	v_mfma_f32_16x16x32_bf16 v[50:53], v[22:25], v[6:9], v[34:37]
	v_mfma_f32_16x16x32_bf16 v[34:37], v[198:201], v[6:9], v[18:21]
	v_mfma_f32_16x16x32_bf16 v[18:21], v[38:41], v[244:247], v[162:165]
	v_mfma_f32_16x16x32_bf16 v[38:41], v[198:201], v[248:251], v[18:21]
	v_mfma_f32_16x16x32_bf16 v[18:21], v[202:205], v[2:5], v[166:169]
	v_mfma_f32_16x16x32_bf16 v[2:5], v[240:243], v[2:5], v[174:177]
	v_mfma_f32_16x16x32_bf16 v[18:21], v[236:239], v[6:9], v[18:21]
	v_mfma_f32_16x16x32_bf16 v[22:25], v[202:205], v[244:247], v[170:173]
	v_mfma_f32_16x16x32_bf16 v[2:5], v[138:141], v[6:9], v[2:5]
	v_mfma_f32_16x16x32_bf16 v[6:9], v[240:243], v[244:247], v[178:181]
	v_mfma_f32_16x16x32_bf16 v[22:25], v[236:239], v[248:251], v[22:25]
	v_mfma_f32_16x16x32_bf16 v[6:9], v[138:141], v[248:251], v[6:9]
	s_setprio 0
	s_and_b64 vcc, exec, s[10:11]
	s_barrier
	s_cbranch_vccz .LBB0_367
	s_barrier

.LBB0_403:
	ds_read_b128 v[134:137], v217
	ds_read_b128 v[138:141], v217 offset:1024
	ds_read_b128 v[142:145], v217 offset:2048
	ds_read_b128 v[146:149], v217 offset:3072
	s_add_u32 s62, s28, s30
	s_addc_u32 s63, s29, s31
	s_add_u32 s60, s62, 0x80
	s_addc_u32 s61, s63, 0
	s_add_i32 s59, s42, 0xc000
	ds_read_b128 v[150:153], v216
	ds_read_b128 v[154:157], v216 offset:1024
	ds_read_b128 v[158:161], v216 offset:2048
	ds_read_b128 v[162:165], v216 offset:3072
	ds_read_b128 v[166:169], v216 offset:4096
	ds_read_b128 v[170:173], v216 offset:5120
	ds_read_b128 v[174:177], v216 offset:6144
	ds_read_b128 v[178:181], v216 offset:7168
	ds_read_b128 v[182:185], v217 offset:16384
	ds_read_b128 v[186:189], v217 offset:17408
	ds_read_b128 v[190:193], v217 offset:18432
	ds_read_b128 v[194:197], v217 offset:19456
	s_mov_b32 m0, s59
	s_add_i32 s58, s42, 0xe000
	global_load_lds_dwordx4 v132, s[60:61]
	s_mov_b32 m0, s58
	s_nop 0
	global_load_lds_dwordx4 v130, s[60:61]
	s_waitcnt lgkmcnt(0)
	s_barrier
	s_setprio 3
	v_mfma_f32_16x16x32_bf16 v[2:5], v[150:153], v[134:137], v[2:5]
	v_mfma_f32_16x16x32_bf16 v[6:9], v[150:153], v[142:145], v[6:9]
	v_mfma_f32_16x16x32_bf16 v[10:13], v[158:161], v[134:137], v[10:13]
	v_mfma_f32_16x16x32_bf16 v[22:25], v[158:161], v[142:145], v[22:25]
	v_mfma_f32_16x16x32_bf16 v[34:37], v[166:169], v[134:137], v[34:37]
	v_mfma_f32_16x16x32_bf16 v[46:49], v[166:169], v[142:145], v[46:49]
	v_mfma_f32_16x16x32_bf16 v[58:61], v[174:177], v[134:137], v[58:61]
	v_mfma_f32_16x16x32_bf16 v[70:73], v[174:177], v[142:145], v[70:73]
	v_mfma_f32_16x16x32_bf16 v[2:5], v[154:157], v[138:141], v[2:5]
	v_mfma_f32_16x16x32_bf16 v[6:9], v[154:157], v[146:149], v[6:9]
	v_mfma_f32_16x16x32_bf16 v[10:13], v[162:165], v[138:141], v[10:13]
	v_mfma_f32_16x16x32_bf16 v[22:25], v[162:165], v[146:149], v[22:25]
	v_mfma_f32_16x16x32_bf16 v[34:37], v[170:173], v[138:141], v[34:37]
	v_mfma_f32_16x16x32_bf16 v[46:49], v[170:173], v[146:149], v[46:49]
	v_mfma_f32_16x16x32_bf16 v[58:61], v[178:181], v[138:141], v[58:61]
	v_mfma_f32_16x16x32_bf16 v[70:73], v[178:181], v[146:149], v[70:73]
	v_mfma_f32_16x16x32_bf16 v[14:17], v[150:153], v[182:185], v[14:17]
	v_mfma_f32_16x16x32_bf16 v[26:29], v[150:153], v[190:193], v[26:29]
	v_mfma_f32_16x16x32_bf16 v[38:41], v[158:161], v[182:185], v[38:41]
	v_mfma_f32_16x16x32_bf16 v[50:53], v[158:161], v[190:193], v[50:53]
	v_mfma_f32_16x16x32_bf16 v[62:65], v[166:169], v[182:185], v[62:65]
	v_mfma_f32_16x16x32_bf16 v[74:77], v[166:169], v[190:193], v[74:77]
	v_mfma_f32_16x16x32_bf16 v[82:85], v[174:177], v[182:185], v[82:85]
	v_mfma_f32_16x16x32_bf16 v[94:97], v[174:177], v[190:193], v[94:97]
	v_mfma_f32_16x16x32_bf16 v[14:17], v[154:157], v[186:189], v[14:17]
	v_mfma_f32_16x16x32_bf16 v[26:29], v[154:157], v[194:197], v[26:29]
	v_mfma_f32_16x16x32_bf16 v[38:41], v[162:165], v[186:189], v[38:41]
	v_mfma_f32_16x16x32_bf16 v[50:53], v[162:165], v[194:197], v[50:53]
	v_mfma_f32_16x16x32_bf16 v[62:65], v[170:173], v[186:189], v[62:65]
	v_mfma_f32_16x16x32_bf16 v[74:77], v[170:173], v[194:197], v[74:77]
	v_mfma_f32_16x16x32_bf16 v[82:85], v[178:181], v[186:189], v[82:85]
	v_mfma_f32_16x16x32_bf16 v[94:97], v[178:181], v[194:197], v[94:97]
	s_setprio 0
	s_barrier
	ds_read_b128 v[150:153], v216 offset:16384
	ds_read_b128 v[154:157], v216 offset:17408
	ds_read_b128 v[158:161], v216 offset:18432
	ds_read_b128 v[162:165], v216 offset:19456
	ds_read_b128 v[166:169], v216 offset:20480
	ds_read_b128 v[170:173], v216 offset:21504
	ds_read_b128 v[174:177], v216 offset:22528
	ds_read_b128 v[178:181], v216 offset:23552
	s_add_i32 s57, s57, 2
	s_add_u32 s64, s22, s30
	s_addc_u32 s65, s23, s31
	s_add_u32 s60, s64, 0x100
	s_addc_u32 s61, s65, 0
	s_mov_b32 m0, s44
	s_nop 0
	global_load_lds_dwordx4 v132, s[60:61]
	s_mov_b32 m0, s45
	s_nop 0
	global_load_lds_dwordx4 v130, s[60:61]
	s_add_u32 s66, s24, s30
	s_addc_u32 s67, s25, s31
	s_add_u32 s60, s66, 0x100
	s_addc_u32 s61, s67, 0
	s_mov_b32 m0, s42
	s_nop 0
	global_load_lds_dwordx4 v132, s[60:61]
	s_mov_b32 m0, s46
	s_nop 0
	global_load_lds_dwordx4 v130, s[60:61]
	s_add_u32 s68, s26, s30
	s_addc_u32 s69, s27, s31
	s_add_u32 s60, s68, 0x100
	s_addc_u32 s61, s69, 0
	s_mov_b32 m0, s47
	s_nop 0
	global_load_lds_dwordx4 v132, s[60:61]
	s_mov_b32 m0, s48
	s_nop 0
	global_load_lds_dwordx4 v130, s[60:61]
	s_waitcnt vmcnt(6)
	s_waitcnt lgkmcnt(0)
	s_barrier
	s_setprio 3
	v_mfma_f32_16x16x32_bf16 v[18:21], v[150:153], v[134:137], v[18:21]
	v_mfma_f32_16x16x32_bf16 v[30:33], v[150:153], v[142:145], v[30:33]
	v_mfma_f32_16x16x32_bf16 v[42:45], v[158:161], v[134:137], v[42:45]
	v_mfma_f32_16x16x32_bf16 v[54:57], v[158:161], v[142:145], v[54:57]
	v_mfma_f32_16x16x32_bf16 v[66:69], v[166:169], v[134:137], v[66:69]
	v_mfma_f32_16x16x32_bf16 v[78:81], v[166:169], v[142:145], v[78:81]
	v_mfma_f32_16x16x32_bf16 v[86:89], v[174:177], v[134:137], v[86:89]
	v_mfma_f32_16x16x32_bf16 v[98:101], v[174:177], v[142:145], v[98:101]
	v_mfma_f32_16x16x32_bf16 v[18:21], v[154:157], v[138:141], v[18:21]
	v_mfma_f32_16x16x32_bf16 v[30:33], v[154:157], v[146:149], v[30:33]
	v_mfma_f32_16x16x32_bf16 v[42:45], v[162:165], v[138:141], v[42:45]
	v_mfma_f32_16x16x32_bf16 v[54:57], v[162:165], v[146:149], v[54:57]
	v_mfma_f32_16x16x32_bf16 v[66:69], v[170:173], v[138:141], v[66:69]
	v_mfma_f32_16x16x32_bf16 v[78:81], v[170:173], v[146:149], v[78:81]
	v_mfma_f32_16x16x32_bf16 v[86:89], v[178:181], v[138:141], v[86:89]
	v_mfma_f32_16x16x32_bf16 v[98:101], v[178:181], v[146:149], v[98:101]
	v_mfma_f32_16x16x32_bf16 v[90:93], v[150:153], v[182:185], v[90:93]
	v_mfma_f32_16x16x32_bf16 v[102:105], v[150:153], v[190:193], v[102:105]
	v_mfma_f32_16x16x32_bf16 v[106:109], v[158:161], v[182:185], v[106:109]
	v_mfma_f32_16x16x32_bf16 v[110:113], v[158:161], v[190:193], v[110:113]
	v_mfma_f32_16x16x32_bf16 v[114:117], v[166:169], v[182:185], v[114:117]
	v_mfma_f32_16x16x32_bf16 v[118:121], v[166:169], v[190:193], v[118:121]
	v_mfma_f32_16x16x32_bf16 v[122:125], v[174:177], v[182:185], v[122:125]
	v_mfma_f32_16x16x32_bf16 v[126:129], v[174:177], v[190:193], v[126:129]
	v_mfma_f32_16x16x32_bf16 v[90:93], v[154:157], v[186:189], v[90:93]
	v_mfma_f32_16x16x32_bf16 v[102:105], v[154:157], v[194:197], v[102:105]
	v_mfma_f32_16x16x32_bf16 v[106:109], v[162:165], v[186:189], v[106:109]
	v_mfma_f32_16x16x32_bf16 v[110:113], v[162:165], v[194:197], v[110:113]
	v_mfma_f32_16x16x32_bf16 v[114:117], v[170:173], v[186:189], v[114:117]
	v_mfma_f32_16x16x32_bf16 v[118:121], v[170:173], v[194:197], v[118:121]
	v_mfma_f32_16x16x32_bf16 v[122:125], v[178:181], v[186:189], v[122:125]
	v_mfma_f32_16x16x32_bf16 v[126:129], v[178:181], v[194:197], v[126:129]
	s_setprio 0
	s_barrier
	ds_read_b128 v[134:137], v217 offset:32768
	ds_read_b128 v[138:141], v217 offset:33792
	ds_read_b128 v[142:145], v217 offset:34816
	ds_read_b128 v[146:149], v217 offset:35840
	s_add_u32 s60, s62, 0x100
	s_addc_u32 s61, s63, 0
	s_mov_b32 m0, s49
	ds_read_b128 v[150:153], v216 offset:32768
	ds_read_b128 v[154:157], v216 offset:33792
	ds_read_b128 v[158:161], v216 offset:34816
	ds_read_b128 v[162:165], v216 offset:35840
	ds_read_b128 v[166:169], v216 offset:36864
	ds_read_b128 v[170:173], v216 offset:37888
	ds_read_b128 v[174:177], v216 offset:38912
	ds_read_b128 v[178:181], v216 offset:39936
	ds_read_b128 v[182:185], v217 offset:49152
	ds_read_b128 v[186:189], v217 offset:50176
	ds_read_b128 v[190:193], v217 offset:51200
	ds_read_b128 v[194:197], v217 offset:52224
	s_nop 0
	global_load_lds_dwordx4 v132, s[60:61]
	s_mov_b32 m0, s50
	s_nop 0
	global_load_lds_dwordx4 v130, s[60:61]
	s_waitcnt lgkmcnt(0)
	s_barrier
	s_setprio 3
	v_mfma_f32_16x16x32_bf16 v[2:5], v[150:153], v[134:137], v[2:5]
	v_mfma_f32_16x16x32_bf16 v[6:9], v[150:153], v[142:145], v[6:9]
	v_mfma_f32_16x16x32_bf16 v[10:13], v[158:161], v[134:137], v[10:13]
	v_mfma_f32_16x16x32_bf16 v[22:25], v[158:161], v[142:145], v[22:25]
	v_mfma_f32_16x16x32_bf16 v[34:37], v[166:169], v[134:137], v[34:37]
	v_mfma_f32_16x16x32_bf16 v[46:49], v[166:169], v[142:145], v[46:49]
	v_mfma_f32_16x16x32_bf16 v[58:61], v[174:177], v[134:137], v[58:61]
	v_mfma_f32_16x16x32_bf16 v[70:73], v[174:177], v[142:145], v[70:73]
	v_mfma_f32_16x16x32_bf16 v[2:5], v[154:157], v[138:141], v[2:5]
	v_mfma_f32_16x16x32_bf16 v[6:9], v[154:157], v[146:149], v[6:9]
	v_mfma_f32_16x16x32_bf16 v[10:13], v[162:165], v[138:141], v[10:13]
	v_mfma_f32_16x16x32_bf16 v[22:25], v[162:165], v[146:149], v[22:25]
	v_mfma_f32_16x16x32_bf16 v[34:37], v[170:173], v[138:141], v[34:37]
	v_mfma_f32_16x16x32_bf16 v[46:49], v[170:173], v[146:149], v[46:49]
	v_mfma_f32_16x16x32_bf16 v[58:61], v[178:181], v[138:141], v[58:61]
	v_mfma_f32_16x16x32_bf16 v[70:73], v[178:181], v[146:149], v[70:73]
	v_mfma_f32_16x16x32_bf16 v[14:17], v[150:153], v[182:185], v[14:17]
	v_mfma_f32_16x16x32_bf16 v[26:29], v[150:153], v[190:193], v[26:29]
	v_mfma_f32_16x16x32_bf16 v[38:41], v[158:161], v[182:185], v[38:41]
	v_mfma_f32_16x16x32_bf16 v[50:53], v[158:161], v[190:193], v[50:53]
	v_mfma_f32_16x16x32_bf16 v[62:65], v[166:169], v[182:185], v[62:65]
	v_mfma_f32_16x16x32_bf16 v[74:77], v[166:169], v[190:193], v[74:77]
	v_mfma_f32_16x16x32_bf16 v[82:85], v[174:177], v[182:185], v[82:85]
	v_mfma_f32_16x16x32_bf16 v[94:97], v[174:177], v[190:193], v[94:97]
	v_mfma_f32_16x16x32_bf16 v[14:17], v[154:157], v[186:189], v[14:17]
	v_mfma_f32_16x16x32_bf16 v[26:29], v[154:157], v[194:197], v[26:29]
	v_mfma_f32_16x16x32_bf16 v[38:41], v[162:165], v[186:189], v[38:41]
	v_mfma_f32_16x16x32_bf16 v[50:53], v[162:165], v[194:197], v[50:53]
	v_mfma_f32_16x16x32_bf16 v[62:65], v[170:173], v[186:189], v[62:65]
	v_mfma_f32_16x16x32_bf16 v[74:77], v[170:173], v[194:197], v[74:77]
	v_mfma_f32_16x16x32_bf16 v[82:85], v[178:181], v[186:189], v[82:85]
	v_mfma_f32_16x16x32_bf16 v[94:97], v[178:181], v[194:197], v[94:97]
	s_setprio 0
	s_barrier
	ds_read_b128 v[150:153], v216 offset:49152
	ds_read_b128 v[154:157], v216 offset:50176
	ds_read_b128 v[158:161], v216 offset:51200
	ds_read_b128 v[162:165], v216 offset:52224
	ds_read_b128 v[166:169], v216 offset:53248
	ds_read_b128 v[170:173], v216 offset:54272
	ds_read_b128 v[174:177], v216 offset:55296
	ds_read_b128 v[178:181], v216 offset:56320
	s_add_u32 s60, s64, 0x180
	s_addc_u32 s61, s65, 0
	s_mov_b32 m0, s51
	s_nop 0
	global_load_lds_dwordx4 v132, s[60:61]
	s_mov_b32 m0, s52
	s_nop 0
	global_load_lds_dwordx4 v130, s[60:61]
	s_add_u32 s60, s66, 0x180
	s_addc_u32 s61, s67, 0
	s_mov_b32 m0, s53
	s_nop 0
	global_load_lds_dwordx4 v132, s[60:61]
	s_mov_b32 m0, s54
	s_nop 0
	global_load_lds_dwordx4 v130, s[60:61]
	s_add_u32 s60, s68, 0x180
	s_addc_u32 s61, s69, 0
	s_mov_b32 m0, s55
	s_nop 0
	global_load_lds_dwordx4 v132, s[60:61]
	s_mov_b32 m0, s56
	s_nop 0
	global_load_lds_dwordx4 v130, s[60:61]
	s_waitcnt vmcnt(6)
	s_waitcnt lgkmcnt(0)
	s_barrier
	s_setprio 3
	v_mfma_f32_16x16x32_bf16 v[18:21], v[150:153], v[134:137], v[18:21]
	v_mfma_f32_16x16x32_bf16 v[30:33], v[150:153], v[142:145], v[30:33]
	v_mfma_f32_16x16x32_bf16 v[42:45], v[158:161], v[134:137], v[42:45]
	v_mfma_f32_16x16x32_bf16 v[54:57], v[158:161], v[142:145], v[54:57]
	v_mfma_f32_16x16x32_bf16 v[66:69], v[166:169], v[134:137], v[66:69]
	v_mfma_f32_16x16x32_bf16 v[78:81], v[166:169], v[142:145], v[78:81]
	v_mfma_f32_16x16x32_bf16 v[86:89], v[174:177], v[134:137], v[86:89]
	v_mfma_f32_16x16x32_bf16 v[98:101], v[174:177], v[142:145], v[98:101]
	v_mfma_f32_16x16x32_bf16 v[18:21], v[154:157], v[138:141], v[18:21]
	v_mfma_f32_16x16x32_bf16 v[30:33], v[154:157], v[146:149], v[30:33]
	v_mfma_f32_16x16x32_bf16 v[42:45], v[162:165], v[138:141], v[42:45]
	v_mfma_f32_16x16x32_bf16 v[54:57], v[162:165], v[146:149], v[54:57]
	v_mfma_f32_16x16x32_bf16 v[66:69], v[170:173], v[138:141], v[66:69]
	v_mfma_f32_16x16x32_bf16 v[78:81], v[170:173], v[146:149], v[78:81]
	v_mfma_f32_16x16x32_bf16 v[86:89], v[178:181], v[138:141], v[86:89]
	v_mfma_f32_16x16x32_bf16 v[98:101], v[178:181], v[146:149], v[98:101]
	v_mfma_f32_16x16x32_bf16 v[90:93], v[150:153], v[182:185], v[90:93]
	v_mfma_f32_16x16x32_bf16 v[102:105], v[150:153], v[190:193], v[102:105]
	v_mfma_f32_16x16x32_bf16 v[106:109], v[158:161], v[182:185], v[106:109]
	v_mfma_f32_16x16x32_bf16 v[110:113], v[158:161], v[190:193], v[110:113]
	v_mfma_f32_16x16x32_bf16 v[114:117], v[166:169], v[182:185], v[114:117]
	v_mfma_f32_16x16x32_bf16 v[118:121], v[166:169], v[190:193], v[118:121]
	v_mfma_f32_16x16x32_bf16 v[122:125], v[174:177], v[182:185], v[122:125]
	v_mfma_f32_16x16x32_bf16 v[126:129], v[174:177], v[190:193], v[126:129]
	v_mfma_f32_16x16x32_bf16 v[90:93], v[154:157], v[186:189], v[90:93]
	v_mfma_f32_16x16x32_bf16 v[102:105], v[154:157], v[194:197], v[102:105]
	v_mfma_f32_16x16x32_bf16 v[106:109], v[162:165], v[186:189], v[106:109]
	v_mfma_f32_16x16x32_bf16 v[110:113], v[162:165], v[194:197], v[110:113]
	v_mfma_f32_16x16x32_bf16 v[114:117], v[170:173], v[186:189], v[114:117]
	v_mfma_f32_16x16x32_bf16 v[118:121], v[170:173], v[194:197], v[118:121]
	v_mfma_f32_16x16x32_bf16 v[122:125], v[178:181], v[186:189], v[122:125]
	v_mfma_f32_16x16x32_bf16 v[126:129], v[178:181], v[194:197], v[126:129]
	s_setprio 0
	s_add_u32 s30, s30, 0x100
	s_addc_u32 s31, s31, 0
	s_cmp_ge_u32 s57, s36
	s_barrier
	s_cbranch_scc0 .LBB0_403
	s_add_u32 s22, s28, s14
	s_addc_u32 s23, s29, s15
	s_mov_b32 m0, s59
	ds_read_b128 v[134:137], v217
	ds_read_b128 v[138:141], v217 offset:1024
	ds_read_b128 v[142:145], v217 offset:2048
	ds_read_b128 v[146:149], v217 offset:3072
	ds_read_b128 v[150:153], v216
	ds_read_b128 v[154:157], v216 offset:1024
	ds_read_b128 v[158:161], v216 offset:2048
	ds_read_b128 v[162:165], v216 offset:3072
	ds_read_b128 v[166:169], v216 offset:4096
	ds_read_b128 v[170:173], v216 offset:5120
	ds_read_b128 v[174:177], v216 offset:6144
	ds_read_b128 v[178:181], v216 offset:7168
	s_nop 0
	global_load_lds_dwordx4 v132, s[22:23]
	s_mov_b32 m0, s58
	s_nop 0
	global_load_lds_dwordx4 v130, s[22:23]
	s_barrier
	s_waitcnt lgkmcnt(0)
	s_setprio 3
	s_waitcnt lgkmcnt(0)
	v_mfma_f32_16x16x32_bf16 v[2:5], v[150:153], v[134:137], v[2:5]
	v_mfma_f32_16x16x32_bf16 v[6:9], v[150:153], v[142:145], v[6:9]
	v_mfma_f32_16x16x32_bf16 v[10:13], v[158:161], v[134:137], v[10:13]
	v_mfma_f32_16x16x32_bf16 v[22:25], v[158:161], v[142:145], v[22:25]
	v_mfma_f32_16x16x32_bf16 v[34:37], v[166:169], v[134:137], v[34:37]
	v_mfma_f32_16x16x32_bf16 v[46:49], v[166:169], v[142:145], v[46:49]
	v_mfma_f32_16x16x32_bf16 v[58:61], v[174:177], v[134:137], v[58:61]
	v_mfma_f32_16x16x32_bf16 v[70:73], v[174:177], v[142:145], v[70:73]
	v_mfma_f32_16x16x32_bf16 v[2:5], v[154:157], v[138:141], v[2:5]
	v_mfma_f32_16x16x32_bf16 v[6:9], v[154:157], v[146:149], v[6:9]
	v_mfma_f32_16x16x32_bf16 v[10:13], v[162:165], v[138:141], v[10:13]
	v_mfma_f32_16x16x32_bf16 v[22:25], v[162:165], v[146:149], v[22:25]
	v_mfma_f32_16x16x32_bf16 v[34:37], v[170:173], v[138:141], v[34:37]
	v_mfma_f32_16x16x32_bf16 v[46:49], v[170:173], v[146:149], v[46:49]
	v_mfma_f32_16x16x32_bf16 v[58:61], v[178:181], v[138:141], v[58:61]
	v_mfma_f32_16x16x32_bf16 v[70:73], v[178:181], v[146:149], v[70:73]
	s_setprio 0
	s_barrier
	ds_read_b128 v[182:185], v217 offset:16384
	ds_read_b128 v[186:189], v217 offset:17408
	ds_read_b128 v[190:193], v217 offset:18432
	ds_read_b128 v[194:197], v217 offset:19456
	s_barrier
	s_waitcnt lgkmcnt(0)
	s_setprio 3
	s_waitcnt lgkmcnt(0)
	v_mfma_f32_16x16x32_bf16 v[74:77], v[166:169], v[190:193], v[74:77]
	v_mfma_f32_16x16x32_bf16 v[14:17], v[150:153], v[182:185], v[14:17]
	v_mfma_f32_16x16x32_bf16 v[26:29], v[150:153], v[190:193], v[26:29]
	v_mfma_f32_16x16x32_bf16 v[38:41], v[158:161], v[182:185], v[38:41]
	v_mfma_f32_16x16x32_bf16 v[50:53], v[158:161], v[190:193], v[50:53]
	v_mfma_f32_16x16x32_bf16 v[62:65], v[166:169], v[182:185], v[62:65]
	v_mfma_f32_16x16x32_bf16 v[150:153], v[170:173], v[194:197], v[74:77]
	v_mfma_f32_16x16x32_bf16 v[74:77], v[174:177], v[182:185], v[82:85]
	v_mfma_f32_16x16x32_bf16 v[14:17], v[154:157], v[186:189], v[14:17]
	v_mfma_f32_16x16x32_bf16 v[26:29], v[154:157], v[194:197], v[26:29]
	v_mfma_f32_16x16x32_bf16 v[38:41], v[162:165], v[186:189], v[38:41]
	v_mfma_f32_16x16x32_bf16 v[50:53], v[162:165], v[194:197], v[50:53]
	v_mfma_f32_16x16x32_bf16 v[62:65], v[170:173], v[186:189], v[62:65]
	v_mfma_f32_16x16x32_bf16 v[154:157], v[178:181], v[186:189], v[74:77]
	v_mfma_f32_16x16x32_bf16 v[74:77], v[174:177], v[190:193], v[94:97]
	v_mfma_f32_16x16x32_bf16 v[158:161], v[178:181], v[194:197], v[74:77]
	s_setprio 0
	s_barrier
	s_nop 4
	ds_read_b128 v[74:77], v216 offset:16384
	ds_read_b128 v[82:85], v216 offset:17408
	ds_read_b128 v[94:97], v216 offset:18432
	ds_read_b128 v[162:165], v216 offset:19456
	ds_read_b128 v[166:169], v216 offset:20480
	ds_read_b128 v[170:173], v216 offset:21504
	ds_read_b128 v[174:177], v216 offset:22528
	ds_read_b128 v[178:181], v216 offset:23552
	s_waitcnt vmcnt(4)
	s_barrier
	s_waitcnt lgkmcnt(0)
	s_setprio 3
	s_waitcnt lgkmcnt(0)
	v_mfma_f32_16x16x32_bf16 v[66:69], v[166:169], v[134:137], v[66:69]
	v_mfma_f32_16x16x32_bf16 v[198:201], v[170:173], v[138:141], v[66:69]
	v_mfma_f32_16x16x32_bf16 v[66:69], v[166:169], v[142:145], v[78:81]
	v_mfma_f32_16x16x32_bf16 v[18:21], v[74:77], v[134:137], v[18:21]
	v_mfma_f32_16x16x32_bf16 v[30:33], v[74:77], v[142:145], v[30:33]
	v_mfma_f32_16x16x32_bf16 v[42:45], v[94:97], v[134:137], v[42:45]
	v_mfma_f32_16x16x32_bf16 v[54:57], v[94:97], v[142:145], v[54:57]
	v_mfma_f32_16x16x32_bf16 v[202:205], v[170:173], v[146:149], v[66:69]
	v_mfma_f32_16x16x32_bf16 v[66:69], v[174:177], v[134:137], v[86:89]
	v_mfma_f32_16x16x32_bf16 v[18:21], v[82:85], v[138:141], v[18:21]
	v_mfma_f32_16x16x32_bf16 v[30:33], v[82:85], v[146:149], v[30:33]
	v_mfma_f32_16x16x32_bf16 v[42:45], v[162:165], v[138:141], v[42:45]
	v_mfma_f32_16x16x32_bf16 v[54:57], v[162:165], v[146:149], v[54:57]
	v_mfma_f32_16x16x32_bf16 v[134:137], v[178:181], v[138:141], v[66:69]
	v_mfma_f32_16x16x32_bf16 v[66:69], v[174:177], v[142:145], v[98:101]
	v_mfma_f32_16x16x32_bf16 v[138:141], v[178:181], v[146:149], v[66:69]
	s_setprio 0
	s_setprio 3
	v_mfma_f32_16x16x32_bf16 v[66:69], v[74:77], v[182:185], v[90:93]
	v_mfma_f32_16x16x32_bf16 v[142:145], v[82:85], v[186:189], v[66:69]
	v_mfma_f32_16x16x32_bf16 v[66:69], v[74:77], v[190:193], v[102:105]
	v_mfma_f32_16x16x32_bf16 v[146:149], v[82:85], v[194:197], v[66:69]
	v_mfma_f32_16x16x32_bf16 v[66:69], v[94:97], v[182:185], v[106:109]
	v_mfma_f32_16x16x32_bf16 v[212:215], v[162:165], v[186:189], v[66:69]
	v_mfma_f32_16x16x32_bf16 v[66:69], v[94:97], v[190:193], v[110:113]
	v_mfma_f32_16x16x32_bf16 v[162:165], v[162:165], v[194:197], v[66:69]
	v_mfma_f32_16x16x32_bf16 v[66:69], v[166:169], v[182:185], v[114:117]
	v_mfma_f32_16x16x32_bf16 v[220:223], v[170:173], v[186:189], v[66:69]
	v_mfma_f32_16x16x32_bf16 v[66:69], v[166:169], v[190:193], v[118:121]
	v_mfma_f32_16x16x32_bf16 v[166:169], v[170:173], v[194:197], v[66:69]
	v_mfma_f32_16x16x32_bf16 v[66:69], v[174:177], v[182:185], v[122:125]
	v_mfma_f32_16x16x32_bf16 v[170:173], v[178:181], v[186:189], v[66:69]
	v_mfma_f32_16x16x32_bf16 v[66:69], v[174:177], v[190:193], v[126:129]
	v_mfma_f32_16x16x32_bf16 v[174:177], v[178:181], v[194:197], v[66:69]
	s_setprio 0
	s_barrier
	ds_read_b128 v[178:181], v217 offset:32768
	ds_read_b128 v[182:185], v217 offset:33792
	ds_read_b128 v[186:189], v217 offset:34816
	ds_read_b128 v[190:193], v217 offset:35840
	s_nop 0
	ds_read_b128 v[66:69], v216 offset:32768
	ds_read_b128 v[82:85], v216 offset:33792
	ds_read_b128 v[86:89], v216 offset:34816
	ds_read_b128 v[102:105], v216 offset:35840
	ds_read_b128 v[194:197], v216 offset:36864
	ds_read_b128 v[224:227], v216 offset:37888
	ds_read_b128 v[228:231], v216 offset:38912
	ds_read_b128 v[232:235], v216 offset:39936
	s_waitcnt vmcnt(2)
	s_barrier
	s_waitcnt lgkmcnt(0)
	s_setprio 3
	s_waitcnt lgkmcnt(0)
	v_mfma_f32_16x16x32_bf16 v[2:5], v[66:69], v[178:181], v[2:5]
	v_mfma_f32_16x16x32_bf16 v[122:125], v[82:85], v[182:185], v[2:5]
	v_mfma_f32_16x16x32_bf16 v[2:5], v[66:69], v[186:189], v[6:9]
	v_mfma_f32_16x16x32_bf16 v[126:129], v[82:85], v[190:193], v[2:5]
	v_mfma_f32_16x16x32_bf16 v[2:5], v[86:89], v[178:181], v[10:13]
	v_mfma_f32_16x16x32_bf16 v[106:109], v[102:105], v[182:185], v[2:5]
	v_mfma_f32_16x16x32_bf16 v[2:5], v[86:89], v[186:189], v[22:25]
	v_mfma_f32_16x16x32_bf16 v[110:113], v[102:105], v[190:193], v[2:5]
	v_mfma_f32_16x16x32_bf16 v[2:5], v[194:197], v[178:181], v[34:37]
	v_mfma_f32_16x16x32_bf16 v[90:93], v[224:227], v[182:185], v[2:5]
	v_mfma_f32_16x16x32_bf16 v[2:5], v[194:197], v[186:189], v[46:49]
	v_mfma_f32_16x16x32_bf16 v[94:97], v[224:227], v[190:193], v[2:5]
	v_mfma_f32_16x16x32_bf16 v[2:5], v[228:231], v[178:181], v[58:61]
	v_mfma_f32_16x16x32_bf16 v[74:77], v[232:235], v[182:185], v[2:5]
	v_mfma_f32_16x16x32_bf16 v[2:5], v[228:231], v[186:189], v[70:73]
	v_mfma_f32_16x16x32_bf16 v[78:81], v[232:235], v[190:193], v[2:5]
	s_setprio 0
	s_barrier
	s_nop 4
	ds_read_b128 v[2:5], v217 offset:49152
	ds_read_b128 v[6:9], v217 offset:50176
	ds_read_b128 v[236:239], v217 offset:51200
	ds_read_b128 v[240:243], v217 offset:52224
	s_waitcnt vmcnt(0)
	s_barrier
	s_waitcnt lgkmcnt(0)
	s_setprio 3
	s_waitcnt lgkmcnt(0)
	v_mfma_f32_16x16x32_bf16 v[10:13], v[66:69], v[2:5], v[14:17]
	v_mfma_f32_16x16x32_bf16 v[114:117], v[82:85], v[6:9], v[10:13]
	v_mfma_f32_16x16x32_bf16 v[10:13], v[66:69], v[236:239], v[26:29]
	v_mfma_f32_16x16x32_bf16 v[118:121], v[82:85], v[240:243], v[10:13]
	v_mfma_f32_16x16x32_bf16 v[10:13], v[86:89], v[2:5], v[38:41]
	v_mfma_f32_16x16x32_bf16 v[98:101], v[102:105], v[6:9], v[10:13]
	v_mfma_f32_16x16x32_bf16 v[10:13], v[86:89], v[236:239], v[50:53]
	v_mfma_f32_16x16x32_bf16 v[102:105], v[102:105], v[240:243], v[10:13]
	v_mfma_f32_16x16x32_bf16 v[10:13], v[194:197], v[2:5], v[62:65]
	v_mfma_f32_16x16x32_bf16 v[82:85], v[224:227], v[6:9], v[10:13]
	v_mfma_f32_16x16x32_bf16 v[10:13], v[194:197], v[236:239], v[150:153]
	v_mfma_f32_16x16x32_bf16 v[86:89], v[224:227], v[240:243], v[10:13]
	v_mfma_f32_16x16x32_bf16 v[10:13], v[228:231], v[2:5], v[154:157]
	v_mfma_f32_16x16x32_bf16 v[66:69], v[232:235], v[6:9], v[10:13]
	v_mfma_f32_16x16x32_bf16 v[10:13], v[228:231], v[236:239], v[158:161]
	v_mfma_f32_16x16x32_bf16 v[70:73], v[232:235], v[240:243], v[10:13]
	s_setprio 0
	s_barrier
	ds_read_b128 v[22:25], v216 offset:49152
	ds_read_b128 v[34:37], v216 offset:50176
	ds_read_b128 v[38:41], v216 offset:51200
	ds_read_b128 v[150:153], v216 offset:52224
	ds_read_b128 v[154:157], v216 offset:53248
	ds_read_b128 v[158:161], v216 offset:54272
	ds_read_b128 v[194:197], v216 offset:55296
	ds_read_b128 v[224:227], v216 offset:56320
	s_barrier
	s_waitcnt lgkmcnt(0)
	s_setprio 3
	s_waitcnt lgkmcnt(0)
	v_mfma_f32_16x16x32_bf16 v[10:13], v[22:25], v[178:181], v[18:21]
	v_mfma_f32_16x16x32_bf16 v[58:61], v[34:37], v[182:185], v[10:13]
	v_mfma_f32_16x16x32_bf16 v[10:13], v[22:25], v[186:189], v[30:33]
	v_mfma_f32_16x16x32_bf16 v[62:65], v[34:37], v[190:193], v[10:13]
	v_mfma_f32_16x16x32_bf16 v[10:13], v[38:41], v[178:181], v[42:45]
	v_mfma_f32_16x16x32_bf16 v[42:45], v[150:153], v[182:185], v[10:13]
	v_mfma_f32_16x16x32_bf16 v[10:13], v[38:41], v[186:189], v[54:57]
	v_mfma_f32_16x16x32_bf16 v[46:49], v[150:153], v[190:193], v[10:13]
	v_mfma_f32_16x16x32_bf16 v[10:13], v[154:157], v[178:181], v[198:201]
	v_mfma_f32_16x16x32_bf16 v[26:29], v[158:161], v[182:185], v[10:13]
	v_mfma_f32_16x16x32_bf16 v[10:13], v[154:157], v[186:189], v[202:205]
	v_mfma_f32_16x16x32_bf16 v[30:33], v[158:161], v[190:193], v[10:13]
	v_mfma_f32_16x16x32_bf16 v[10:13], v[194:197], v[178:181], v[134:137]
	v_mfma_f32_16x16x32_bf16 v[14:17], v[194:197], v[186:189], v[138:141]
	v_mfma_f32_16x16x32_bf16 v[10:13], v[224:227], v[182:185], v[10:13]
	v_mfma_f32_16x16x32_bf16 v[14:17], v[224:227], v[190:193], v[14:17]
	s_setprio 0
	s_setprio 3
	v_mfma_f32_16x16x32_bf16 v[18:21], v[22:25], v[2:5], v[142:145]
	v_mfma_f32_16x16x32_bf16 v[50:53], v[34:37], v[6:9], v[18:21]
	v_mfma_f32_16x16x32_bf16 v[18:21], v[22:25], v[236:239], v[146:149]
	v_mfma_f32_16x16x32_bf16 v[54:57], v[34:37], v[240:243], v[18:21]
	v_mfma_f32_16x16x32_bf16 v[18:21], v[38:41], v[2:5], v[212:215]
	v_mfma_f32_16x16x32_bf16 v[34:37], v[150:153], v[6:9], v[18:21]
	v_mfma_f32_16x16x32_bf16 v[18:21], v[38:41], v[236:239], v[162:165]
	v_mfma_f32_16x16x32_bf16 v[38:41], v[150:153], v[240:243], v[18:21]
	v_mfma_f32_16x16x32_bf16 v[18:21], v[154:157], v[2:5], v[220:223]
	v_mfma_f32_16x16x32_bf16 v[2:5], v[194:197], v[2:5], v[170:173]
	v_mfma_f32_16x16x32_bf16 v[18:21], v[158:161], v[6:9], v[18:21]
	v_mfma_f32_16x16x32_bf16 v[22:25], v[154:157], v[236:239], v[166:169]
	v_mfma_f32_16x16x32_bf16 v[2:5], v[224:227], v[6:9], v[2:5]
	v_mfma_f32_16x16x32_bf16 v[6:9], v[194:197], v[236:239], v[174:177]
	v_mfma_f32_16x16x32_bf16 v[22:25], v[158:161], v[240:243], v[22:25]
	v_mfma_f32_16x16x32_bf16 v[6:9], v[224:227], v[240:243], v[6:9]
	s_setprio 0
	s_and_b64 vcc, exec, s[16:17]
	s_barrier
	s_cbranch_vccz .LBB0_406
	s_barrier

.LBB0_468:
	ds_read_b128 v[138:141], v137
	ds_read_b128 v[142:145], v137 offset:1024
	ds_read_b128 v[146:149], v137 offset:2048
	ds_read_b128 v[150:153], v137 offset:3072
	s_add_u32 s57, s18, s16
	s_addc_u32 s60, s19, s17
	s_add_u32 s58, s57, 0x180
	s_addc_u32 s59, s60, 0
	s_mov_b32 m0, s40
	ds_read_b128 v[154:157], v136
	ds_read_b128 v[158:161], v136 offset:1024
	ds_read_b128 v[162:165], v136 offset:2048
	ds_read_b128 v[166:169], v136 offset:3072
	ds_read_b128 v[170:173], v136 offset:4096
	ds_read_b128 v[174:177], v136 offset:5120
	ds_read_b128 v[178:181], v136 offset:6144
	ds_read_b128 v[182:185], v136 offset:7168
	ds_read_b128 v[186:189], v137 offset:16384
	ds_read_b128 v[190:193], v137 offset:17408
	ds_read_b128 v[194:197], v137 offset:18432
	ds_read_b128 v[198:201], v137 offset:19456
	s_nop 0
	global_load_lds_dwordx4 v130, s[58:59]
	s_mov_b32 m0, s41
	s_nop 0
	global_load_lds_dwordx4 v132, s[58:59]
	s_waitcnt lgkmcnt(0)
	s_barrier
	s_setprio 3
	v_mfma_f32_16x16x32_bf16 v[30:33], v[154:157], v[138:141], v[30:33]
	v_mfma_f32_16x16x32_bf16 v[26:29], v[154:157], v[146:149], v[26:29]
	v_mfma_f32_16x16x32_bf16 v[22:25], v[162:165], v[138:141], v[22:25]
	v_mfma_f32_16x16x32_bf16 v[18:21], v[162:165], v[146:149], v[18:21]
	v_mfma_f32_16x16x32_bf16 v[14:17], v[170:173], v[138:141], v[14:17]
	v_mfma_f32_16x16x32_bf16 v[10:13], v[170:173], v[146:149], v[10:13]
	v_mfma_f32_16x16x32_bf16 v[6:9], v[178:181], v[138:141], v[6:9]
	v_mfma_f32_16x16x32_bf16 v[2:5], v[178:181], v[146:149], v[2:5]
	v_mfma_f32_16x16x32_bf16 v[30:33], v[158:161], v[142:145], v[30:33]
	v_mfma_f32_16x16x32_bf16 v[26:29], v[158:161], v[150:153], v[26:29]
	v_mfma_f32_16x16x32_bf16 v[22:25], v[166:169], v[142:145], v[22:25]
	v_mfma_f32_16x16x32_bf16 v[18:21], v[166:169], v[150:153], v[18:21]
	v_mfma_f32_16x16x32_bf16 v[14:17], v[174:177], v[142:145], v[14:17]
	v_mfma_f32_16x16x32_bf16 v[10:13], v[174:177], v[150:153], v[10:13]
	v_mfma_f32_16x16x32_bf16 v[6:9], v[182:185], v[142:145], v[6:9]
	v_mfma_f32_16x16x32_bf16 v[2:5], v[182:185], v[150:153], v[2:5]
	v_mfma_f32_16x16x32_bf16 v[62:65], v[154:157], v[186:189], v[62:65]
	v_mfma_f32_16x16x32_bf16 v[58:61], v[154:157], v[194:197], v[58:61]
	v_mfma_f32_16x16x32_bf16 v[54:57], v[162:165], v[186:189], v[54:57]
	v_mfma_f32_16x16x32_bf16 v[50:53], v[162:165], v[194:197], v[50:53]
	v_mfma_f32_16x16x32_bf16 v[46:49], v[170:173], v[186:189], v[46:49]
	v_mfma_f32_16x16x32_bf16 v[42:45], v[170:173], v[194:197], v[42:45]
	v_mfma_f32_16x16x32_bf16 v[38:41], v[178:181], v[186:189], v[38:41]
	v_mfma_f32_16x16x32_bf16 v[34:37], v[178:181], v[194:197], v[34:37]
	v_mfma_f32_16x16x32_bf16 v[62:65], v[158:161], v[190:193], v[62:65]
	v_mfma_f32_16x16x32_bf16 v[58:61], v[158:161], v[198:201], v[58:61]
	v_mfma_f32_16x16x32_bf16 v[54:57], v[166:169], v[190:193], v[54:57]
	v_mfma_f32_16x16x32_bf16 v[50:53], v[166:169], v[198:201], v[50:53]
	v_mfma_f32_16x16x32_bf16 v[46:49], v[174:177], v[190:193], v[46:49]
	v_mfma_f32_16x16x32_bf16 v[42:45], v[174:177], v[198:201], v[42:45]
	v_mfma_f32_16x16x32_bf16 v[38:41], v[182:185], v[190:193], v[38:41]
	v_mfma_f32_16x16x32_bf16 v[34:37], v[182:185], v[198:201], v[34:37]
	s_setprio 0
	s_barrier
	ds_read_b128 v[154:157], v136 offset:16384
	ds_read_b128 v[158:161], v136 offset:17408
	ds_read_b128 v[162:165], v136 offset:18432
	ds_read_b128 v[166:169], v136 offset:19456
	ds_read_b128 v[170:173], v136 offset:20480
	ds_read_b128 v[174:177], v136 offset:21504
	ds_read_b128 v[178:181], v136 offset:22528
	ds_read_b128 v[182:185], v136 offset:23552
	s_add_u32 s61, s51, s16
	s_addc_u32 s62, s52, s17
	s_add_u32 s58, s61, 0x200
	s_addc_u32 s59, s62, 0
	s_mov_b32 m0, s26
	s_nop 0
	global_load_lds_dwordx4 v130, s[58:59]
	s_mov_b32 m0, s27
	s_nop 0
	global_load_lds_dwordx4 v132, s[58:59]
	s_add_u32 s63, s13, s16
	s_addc_u32 s64, s53, s17
	s_add_u32 s58, s63, 0x200
	s_addc_u32 s59, s64, 0
	s_mov_b32 m0, s25
	s_nop 0
	global_load_lds_dwordx4 v130, s[58:59]
	s_mov_b32 m0, s28
	s_nop 0
	global_load_lds_dwordx4 v132, s[58:59]
	s_add_u32 s65, s54, s16
	s_addc_u32 s66, s55, s17
	s_add_u32 s58, s65, 0x200
	s_addc_u32 s59, s66, 0
	s_mov_b32 m0, s29
	s_nop 0
	global_load_lds_dwordx4 v130, s[58:59]
	s_mov_b32 m0, s30
	s_nop 0
	global_load_lds_dwordx4 v132, s[58:59]
	s_waitcnt vmcnt(6)
	s_waitcnt lgkmcnt(0)
	s_barrier
	s_setprio 3
	v_mfma_f32_16x16x32_bf16 v[94:97], v[154:157], v[138:141], v[94:97]
	v_mfma_f32_16x16x32_bf16 v[90:93], v[154:157], v[146:149], v[90:93]
	v_mfma_f32_16x16x32_bf16 v[86:89], v[162:165], v[138:141], v[86:89]
	v_mfma_f32_16x16x32_bf16 v[82:85], v[162:165], v[146:149], v[82:85]
	v_mfma_f32_16x16x32_bf16 v[78:81], v[170:173], v[138:141], v[78:81]
	v_mfma_f32_16x16x32_bf16 v[74:77], v[170:173], v[146:149], v[74:77]
	v_mfma_f32_16x16x32_bf16 v[70:73], v[178:181], v[138:141], v[70:73]
	v_mfma_f32_16x16x32_bf16 v[66:69], v[178:181], v[146:149], v[66:69]
	v_mfma_f32_16x16x32_bf16 v[94:97], v[158:161], v[142:145], v[94:97]
	v_mfma_f32_16x16x32_bf16 v[90:93], v[158:161], v[150:153], v[90:93]
	v_mfma_f32_16x16x32_bf16 v[86:89], v[166:169], v[142:145], v[86:89]
	v_mfma_f32_16x16x32_bf16 v[82:85], v[166:169], v[150:153], v[82:85]
	v_mfma_f32_16x16x32_bf16 v[78:81], v[174:177], v[142:145], v[78:81]
	v_mfma_f32_16x16x32_bf16 v[74:77], v[174:177], v[150:153], v[74:77]
	v_mfma_f32_16x16x32_bf16 v[70:73], v[182:185], v[142:145], v[70:73]
	v_mfma_f32_16x16x32_bf16 v[66:69], v[182:185], v[150:153], v[66:69]
	v_mfma_f32_16x16x32_bf16 v[126:129], v[154:157], v[186:189], v[126:129]
	v_mfma_f32_16x16x32_bf16 v[122:125], v[154:157], v[194:197], v[122:125]
	v_mfma_f32_16x16x32_bf16 v[118:121], v[162:165], v[186:189], v[118:121]
	v_mfma_f32_16x16x32_bf16 v[114:117], v[162:165], v[194:197], v[114:117]
	v_mfma_f32_16x16x32_bf16 v[110:113], v[170:173], v[186:189], v[110:113]
	v_mfma_f32_16x16x32_bf16 v[106:109], v[170:173], v[194:197], v[106:109]
	v_mfma_f32_16x16x32_bf16 v[102:105], v[178:181], v[186:189], v[102:105]
	v_mfma_f32_16x16x32_bf16 v[98:101], v[178:181], v[194:197], v[98:101]
	v_mfma_f32_16x16x32_bf16 v[126:129], v[158:161], v[190:193], v[126:129]
	v_mfma_f32_16x16x32_bf16 v[122:125], v[158:161], v[198:201], v[122:125]
	v_mfma_f32_16x16x32_bf16 v[118:121], v[166:169], v[190:193], v[118:121]
	v_mfma_f32_16x16x32_bf16 v[114:117], v[166:169], v[198:201], v[114:117]
	v_mfma_f32_16x16x32_bf16 v[110:113], v[174:177], v[190:193], v[110:113]
	v_mfma_f32_16x16x32_bf16 v[106:109], v[174:177], v[198:201], v[106:109]
	v_mfma_f32_16x16x32_bf16 v[102:105], v[182:185], v[190:193], v[102:105]
	v_mfma_f32_16x16x32_bf16 v[98:101], v[182:185], v[198:201], v[98:101]
	s_setprio 0
	s_barrier
	ds_read_b128 v[138:141], v137 offset:32768
	ds_read_b128 v[142:145], v137 offset:33792
	ds_read_b128 v[146:149], v137 offset:34816
	ds_read_b128 v[150:153], v137 offset:35840
	s_add_u32 s58, s57, 0x200
	s_addc_u32 s59, s60, 0
	s_mov_b32 m0, s31
	ds_read_b128 v[154:157], v136 offset:32768
	ds_read_b128 v[158:161], v136 offset:33792
	ds_read_b128 v[162:165], v136 offset:34816
	ds_read_b128 v[166:169], v136 offset:35840
	ds_read_b128 v[170:173], v136 offset:36864
	ds_read_b128 v[174:177], v136 offset:37888
	ds_read_b128 v[178:181], v136 offset:38912
	ds_read_b128 v[182:185], v136 offset:39936
	ds_read_b128 v[186:189], v137 offset:49152
	ds_read_b128 v[190:193], v137 offset:50176
	ds_read_b128 v[194:197], v137 offset:51200
	ds_read_b128 v[198:201], v137 offset:52224
	s_nop 0
	global_load_lds_dwordx4 v130, s[58:59]
	s_mov_b32 m0, s33
	s_nop 0
	global_load_lds_dwordx4 v132, s[58:59]
	s_waitcnt lgkmcnt(0)
	s_barrier
	s_setprio 3
	v_mfma_f32_16x16x32_bf16 v[30:33], v[154:157], v[138:141], v[30:33]
	v_mfma_f32_16x16x32_bf16 v[26:29], v[154:157], v[146:149], v[26:29]
	v_mfma_f32_16x16x32_bf16 v[22:25], v[162:165], v[138:141], v[22:25]
	v_mfma_f32_16x16x32_bf16 v[18:21], v[162:165], v[146:149], v[18:21]
	v_mfma_f32_16x16x32_bf16 v[14:17], v[170:173], v[138:141], v[14:17]
	v_mfma_f32_16x16x32_bf16 v[10:13], v[170:173], v[146:149], v[10:13]
	v_mfma_f32_16x16x32_bf16 v[6:9], v[178:181], v[138:141], v[6:9]
	v_mfma_f32_16x16x32_bf16 v[2:5], v[178:181], v[146:149], v[2:5]
	v_mfma_f32_16x16x32_bf16 v[30:33], v[158:161], v[142:145], v[30:33]
	v_mfma_f32_16x16x32_bf16 v[26:29], v[158:161], v[150:153], v[26:29]
	v_mfma_f32_16x16x32_bf16 v[22:25], v[166:169], v[142:145], v[22:25]
	v_mfma_f32_16x16x32_bf16 v[18:21], v[166:169], v[150:153], v[18:21]
	v_mfma_f32_16x16x32_bf16 v[14:17], v[174:177], v[142:145], v[14:17]
	v_mfma_f32_16x16x32_bf16 v[10:13], v[174:177], v[150:153], v[10:13]
	v_mfma_f32_16x16x32_bf16 v[6:9], v[182:185], v[142:145], v[6:9]
	v_mfma_f32_16x16x32_bf16 v[2:5], v[182:185], v[150:153], v[2:5]
	v_mfma_f32_16x16x32_bf16 v[62:65], v[154:157], v[186:189], v[62:65]
	v_mfma_f32_16x16x32_bf16 v[58:61], v[154:157], v[194:197], v[58:61]
	v_mfma_f32_16x16x32_bf16 v[54:57], v[162:165], v[186:189], v[54:57]
	v_mfma_f32_16x16x32_bf16 v[50:53], v[162:165], v[194:197], v[50:53]
	v_mfma_f32_16x16x32_bf16 v[46:49], v[170:173], v[186:189], v[46:49]
	v_mfma_f32_16x16x32_bf16 v[42:45], v[170:173], v[194:197], v[42:45]
	v_mfma_f32_16x16x32_bf16 v[38:41], v[178:181], v[186:189], v[38:41]
	v_mfma_f32_16x16x32_bf16 v[34:37], v[178:181], v[194:197], v[34:37]
	v_mfma_f32_16x16x32_bf16 v[62:65], v[158:161], v[190:193], v[62:65]
	v_mfma_f32_16x16x32_bf16 v[58:61], v[158:161], v[198:201], v[58:61]
	v_mfma_f32_16x16x32_bf16 v[54:57], v[166:169], v[190:193], v[54:57]
	v_mfma_f32_16x16x32_bf16 v[50:53], v[166:169], v[198:201], v[50:53]
	v_mfma_f32_16x16x32_bf16 v[46:49], v[174:177], v[190:193], v[46:49]
	v_mfma_f32_16x16x32_bf16 v[42:45], v[174:177], v[198:201], v[42:45]
	v_mfma_f32_16x16x32_bf16 v[38:41], v[182:185], v[190:193], v[38:41]
	v_mfma_f32_16x16x32_bf16 v[34:37], v[182:185], v[198:201], v[34:37]
	s_setprio 0
	s_barrier
	ds_read_b128 v[154:157], v136 offset:49152
	ds_read_b128 v[158:161], v136 offset:50176
	ds_read_b128 v[162:165], v136 offset:51200
	ds_read_b128 v[166:169], v136 offset:52224
	ds_read_b128 v[170:173], v136 offset:53248
	ds_read_b128 v[174:177], v136 offset:54272
	ds_read_b128 v[178:181], v136 offset:55296
	ds_read_b128 v[182:185], v136 offset:56320
	s_add_u32 s58, s61, 0x280
	s_addc_u32 s59, s62, 0
	s_mov_b32 m0, s34
	s_nop 0
	global_load_lds_dwordx4 v130, s[58:59]
	s_mov_b32 m0, s35
	s_nop 0
	global_load_lds_dwordx4 v132, s[58:59]
	s_add_u32 s58, s63, 0x280
	s_addc_u32 s59, s64, 0
	s_mov_b32 m0, s36
	s_nop 0
	global_load_lds_dwordx4 v130, s[58:59]
	s_mov_b32 m0, s37
	s_nop 0
	global_load_lds_dwordx4 v132, s[58:59]
	s_add_u32 s58, s65, 0x280
	s_addc_u32 s59, s66, 0
	s_mov_b32 m0, s38
	s_nop 0
	global_load_lds_dwordx4 v130, s[58:59]
	s_mov_b32 m0, s39
	s_nop 0
	global_load_lds_dwordx4 v132, s[58:59]
	s_waitcnt vmcnt(6)
	s_waitcnt lgkmcnt(0)
	s_barrier
	s_setprio 3
	v_mfma_f32_16x16x32_bf16 v[94:97], v[154:157], v[138:141], v[94:97]
	v_mfma_f32_16x16x32_bf16 v[90:93], v[154:157], v[146:149], v[90:93]
	v_mfma_f32_16x16x32_bf16 v[86:89], v[162:165], v[138:141], v[86:89]
	v_mfma_f32_16x16x32_bf16 v[82:85], v[162:165], v[146:149], v[82:85]
	v_mfma_f32_16x16x32_bf16 v[78:81], v[170:173], v[138:141], v[78:81]
	v_mfma_f32_16x16x32_bf16 v[74:77], v[170:173], v[146:149], v[74:77]
	v_mfma_f32_16x16x32_bf16 v[70:73], v[178:181], v[138:141], v[70:73]
	v_mfma_f32_16x16x32_bf16 v[66:69], v[178:181], v[146:149], v[66:69]
	v_mfma_f32_16x16x32_bf16 v[94:97], v[158:161], v[142:145], v[94:97]
	v_mfma_f32_16x16x32_bf16 v[90:93], v[158:161], v[150:153], v[90:93]
	v_mfma_f32_16x16x32_bf16 v[86:89], v[166:169], v[142:145], v[86:89]
	v_mfma_f32_16x16x32_bf16 v[82:85], v[166:169], v[150:153], v[82:85]
	v_mfma_f32_16x16x32_bf16 v[78:81], v[174:177], v[142:145], v[78:81]
	v_mfma_f32_16x16x32_bf16 v[74:77], v[174:177], v[150:153], v[74:77]
	v_mfma_f32_16x16x32_bf16 v[70:73], v[182:185], v[142:145], v[70:73]
	v_mfma_f32_16x16x32_bf16 v[66:69], v[182:185], v[150:153], v[66:69]
	v_mfma_f32_16x16x32_bf16 v[126:129], v[154:157], v[186:189], v[126:129]
	v_mfma_f32_16x16x32_bf16 v[122:125], v[154:157], v[194:197], v[122:125]
	v_mfma_f32_16x16x32_bf16 v[118:121], v[162:165], v[186:189], v[118:121]
	v_mfma_f32_16x16x32_bf16 v[114:117], v[162:165], v[194:197], v[114:117]
	v_mfma_f32_16x16x32_bf16 v[110:113], v[170:173], v[186:189], v[110:113]
	v_mfma_f32_16x16x32_bf16 v[106:109], v[170:173], v[194:197], v[106:109]
	v_mfma_f32_16x16x32_bf16 v[102:105], v[178:181], v[186:189], v[102:105]
	v_mfma_f32_16x16x32_bf16 v[98:101], v[178:181], v[194:197], v[98:101]
	v_mfma_f32_16x16x32_bf16 v[126:129], v[158:161], v[190:193], v[126:129]
	v_mfma_f32_16x16x32_bf16 v[122:125], v[158:161], v[198:201], v[122:125]
	v_mfma_f32_16x16x32_bf16 v[118:121], v[166:169], v[190:193], v[118:121]
	v_mfma_f32_16x16x32_bf16 v[114:117], v[166:169], v[198:201], v[114:117]
	v_mfma_f32_16x16x32_bf16 v[110:113], v[174:177], v[190:193], v[110:113]
	v_mfma_f32_16x16x32_bf16 v[106:109], v[174:177], v[198:201], v[106:109]
	v_mfma_f32_16x16x32_bf16 v[102:105], v[182:185], v[190:193], v[102:105]
	v_mfma_f32_16x16x32_bf16 v[98:101], v[182:185], v[198:201], v[98:101]
	s_setprio 0
	s_add_i32 s56, s56, 2
	s_add_u32 s16, s16, 0x100
	s_addc_u32 s17, s17, 0
	s_cmp_gt_u32 s56, 11
	s_barrier
	s_cbranch_scc0 .LBB0_468
	s_lshl_b64 s[14:15], s[14:15], 1
	s_add_u32 s14, s42, s14
	s_addc_u32 s15, s43, s15
	s_mov_b32 m0, s40
	ds_read_b128 v[142:145], v137
	ds_read_b128 v[146:149], v137 offset:1024
	ds_read_b128 v[150:153], v137 offset:2048
	ds_read_b128 v[154:157], v137 offset:3072
	ds_read_b128 v[158:161], v136
	ds_read_b128 v[162:165], v136 offset:1024
	ds_read_b128 v[166:169], v136 offset:2048
	ds_read_b128 v[170:173], v136 offset:3072
	ds_read_b128 v[174:177], v136 offset:4096
	ds_read_b128 v[178:181], v136 offset:5120
	ds_read_b128 v[182:185], v136 offset:6144
	ds_read_b128 v[186:189], v136 offset:7168
	s_nop 0
	global_load_lds_dwordx4 v130, s[14:15]
	s_mov_b32 m0, s41
	s_nop 0
	global_load_lds_dwordx4 v132, s[14:15]
	s_barrier
	s_waitcnt lgkmcnt(0)
	s_setprio 3
	s_waitcnt lgkmcnt(0)
	v_mfma_f32_16x16x32_bf16 v[30:33], v[158:161], v[142:145], v[30:33]
	v_mfma_f32_16x16x32_bf16 v[26:29], v[158:161], v[150:153], v[26:29]
	v_mfma_f32_16x16x32_bf16 v[22:25], v[166:169], v[142:145], v[22:25]
	v_mfma_f32_16x16x32_bf16 v[18:21], v[166:169], v[150:153], v[18:21]
	v_mfma_f32_16x16x32_bf16 v[14:17], v[174:177], v[142:145], v[14:17]
	v_mfma_f32_16x16x32_bf16 v[10:13], v[174:177], v[150:153], v[10:13]
	v_mfma_f32_16x16x32_bf16 v[6:9], v[182:185], v[142:145], v[6:9]
	v_mfma_f32_16x16x32_bf16 v[2:5], v[182:185], v[150:153], v[2:5]
	v_mfma_f32_16x16x32_bf16 v[30:33], v[162:165], v[146:149], v[30:33]
	v_mfma_f32_16x16x32_bf16 v[26:29], v[162:165], v[154:157], v[26:29]
	v_mfma_f32_16x16x32_bf16 v[22:25], v[170:173], v[146:149], v[22:25]
	v_mfma_f32_16x16x32_bf16 v[18:21], v[170:173], v[154:157], v[18:21]
	v_mfma_f32_16x16x32_bf16 v[14:17], v[178:181], v[146:149], v[14:17]
	v_mfma_f32_16x16x32_bf16 v[10:13], v[178:181], v[154:157], v[10:13]
	v_mfma_f32_16x16x32_bf16 v[6:9], v[186:189], v[146:149], v[6:9]
	v_mfma_f32_16x16x32_bf16 v[2:5], v[186:189], v[154:157], v[2:5]
	s_setprio 0
	s_barrier
	ds_read_b128 v[190:193], v137 offset:16384
	ds_read_b128 v[194:197], v137 offset:17408
	ds_read_b128 v[198:201], v137 offset:18432
	ds_read_b128 v[202:205], v137 offset:19456
	s_barrier
	s_waitcnt lgkmcnt(0)
	s_setprio 3
	s_waitcnt lgkmcnt(0)
	v_mfma_f32_16x16x32_bf16 v[62:65], v[158:161], v[190:193], v[62:65]
	v_mfma_f32_16x16x32_bf16 v[58:61], v[158:161], v[198:201], v[58:61]
	v_mfma_f32_16x16x32_bf16 v[54:57], v[166:169], v[190:193], v[54:57]
	v_mfma_f32_16x16x32_bf16 v[50:53], v[166:169], v[198:201], v[50:53]
	v_mfma_f32_16x16x32_bf16 v[46:49], v[174:177], v[190:193], v[46:49]
	v_mfma_f32_16x16x32_bf16 v[42:45], v[174:177], v[198:201], v[42:45]
	v_mfma_f32_16x16x32_bf16 v[38:41], v[182:185], v[190:193], v[38:41]
	v_mfma_f32_16x16x32_bf16 v[34:37], v[182:185], v[198:201], v[34:37]
	v_mfma_f32_16x16x32_bf16 v[62:65], v[162:165], v[194:197], v[62:65]
	v_mfma_f32_16x16x32_bf16 v[58:61], v[162:165], v[202:205], v[58:61]
	v_mfma_f32_16x16x32_bf16 v[54:57], v[170:173], v[194:197], v[54:57]
	v_mfma_f32_16x16x32_bf16 v[50:53], v[170:173], v[202:205], v[50:53]
	v_mfma_f32_16x16x32_bf16 v[46:49], v[178:181], v[194:197], v[46:49]
	v_mfma_f32_16x16x32_bf16 v[42:45], v[178:181], v[202:205], v[42:45]
	v_mfma_f32_16x16x32_bf16 v[38:41], v[186:189], v[194:197], v[38:41]
	v_mfma_f32_16x16x32_bf16 v[34:37], v[186:189], v[202:205], v[34:37]
	s_setprio 0
	s_barrier
	ds_read_b128 v[158:161], v136 offset:16384
	ds_read_b128 v[162:165], v136 offset:17408
	ds_read_b128 v[166:169], v136 offset:18432
	ds_read_b128 v[170:173], v136 offset:19456
	ds_read_b128 v[174:177], v136 offset:20480
	ds_read_b128 v[178:181], v136 offset:21504
	ds_read_b128 v[182:185], v136 offset:22528
	ds_read_b128 v[186:189], v136 offset:23552
	s_waitcnt vmcnt(4)
	s_barrier
	s_waitcnt lgkmcnt(0)
	s_setprio 3
	s_waitcnt lgkmcnt(0)
	v_mfma_f32_16x16x32_bf16 v[94:97], v[158:161], v[142:145], v[94:97]
	v_mfma_f32_16x16x32_bf16 v[90:93], v[158:161], v[150:153], v[90:93]
	v_mfma_f32_16x16x32_bf16 v[86:89], v[166:169], v[142:145], v[86:89]
	v_mfma_f32_16x16x32_bf16 v[82:85], v[166:169], v[150:153], v[82:85]
	v_mfma_f32_16x16x32_bf16 v[78:81], v[174:177], v[142:145], v[78:81]
	v_mfma_f32_16x16x32_bf16 v[74:77], v[174:177], v[150:153], v[74:77]
	v_mfma_f32_16x16x32_bf16 v[70:73], v[182:185], v[142:145], v[70:73]
	v_mfma_f32_16x16x32_bf16 v[66:69], v[182:185], v[150:153], v[66:69]
	v_mfma_f32_16x16x32_bf16 v[216:219], v[162:165], v[146:149], v[94:97]
	v_mfma_f32_16x16x32_bf16 v[220:223], v[162:165], v[154:157], v[90:93]
	v_mfma_f32_16x16x32_bf16 v[224:227], v[170:173], v[146:149], v[86:89]
	v_mfma_f32_16x16x32_bf16 v[228:231], v[170:173], v[154:157], v[82:85]
	v_mfma_f32_16x16x32_bf16 v[232:235], v[178:181], v[146:149], v[78:81]
	v_mfma_f32_16x16x32_bf16 v[236:239], v[178:181], v[154:157], v[74:77]
	v_mfma_f32_16x16x32_bf16 v[142:145], v[186:189], v[146:149], v[70:73]
	v_mfma_f32_16x16x32_bf16 v[146:149], v[186:189], v[154:157], v[66:69]
	s_setprio 0
	s_setprio 3
	v_mfma_f32_16x16x32_bf16 v[66:69], v[158:161], v[190:193], v[126:129]
	v_mfma_f32_16x16x32_bf16 v[150:153], v[162:165], v[194:197], v[66:69]
	v_mfma_f32_16x16x32_bf16 v[66:69], v[158:161], v[198:201], v[122:125]
	v_mfma_f32_16x16x32_bf16 v[154:157], v[162:165], v[202:205], v[66:69]
	v_mfma_f32_16x16x32_bf16 v[66:69], v[166:169], v[190:193], v[118:121]
	v_mfma_f32_16x16x32_bf16 v[158:161], v[170:173], v[194:197], v[66:69]
	v_mfma_f32_16x16x32_bf16 v[66:69], v[166:169], v[198:201], v[114:117]
	v_mfma_f32_16x16x32_bf16 v[162:165], v[170:173], v[202:205], v[66:69]
	v_mfma_f32_16x16x32_bf16 v[66:69], v[174:177], v[190:193], v[110:113]
	v_mfma_f32_16x16x32_bf16 v[166:169], v[178:181], v[194:197], v[66:69]
	v_mfma_f32_16x16x32_bf16 v[66:69], v[174:177], v[198:201], v[106:109]
	v_mfma_f32_16x16x32_bf16 v[170:173], v[178:181], v[202:205], v[66:69]
	v_mfma_f32_16x16x32_bf16 v[66:69], v[182:185], v[190:193], v[102:105]
	v_mfma_f32_16x16x32_bf16 v[174:177], v[186:189], v[194:197], v[66:69]
	v_mfma_f32_16x16x32_bf16 v[66:69], v[182:185], v[198:201], v[98:101]
	v_mfma_f32_16x16x32_bf16 v[178:181], v[186:189], v[202:205], v[66:69]
	s_setprio 0
	s_barrier
	ds_read_b128 v[182:185], v137 offset:32768
	ds_read_b128 v[186:189], v137 offset:33792
	ds_read_b128 v[190:193], v137 offset:34816
	ds_read_b128 v[194:197], v137 offset:35840
	ds_read_b128 v[74:77], v136 offset:32768
	ds_read_b128 v[78:81], v136 offset:33792
	ds_read_b128 v[90:93], v136 offset:34816
	ds_read_b128 v[94:97], v136 offset:35840
	ds_read_b128 v[198:201], v136 offset:36864
	ds_read_b128 v[202:205], v136 offset:37888
	ds_read_b128 v[240:243], v136 offset:38912
	ds_read_b128 v[244:247], v136 offset:39936
	s_waitcnt vmcnt(2)
	s_barrier
	s_waitcnt lgkmcnt(0)
	s_setprio 3
	s_waitcnt lgkmcnt(0)
	v_mfma_f32_16x16x32_bf16 v[30:33], v[74:77], v[182:185], v[30:33]
	v_mfma_f32_16x16x32_bf16 v[26:29], v[74:77], v[190:193], v[26:29]
	v_mfma_f32_16x16x32_bf16 v[22:25], v[90:93], v[182:185], v[22:25]
	v_mfma_f32_16x16x32_bf16 v[18:21], v[90:93], v[190:193], v[18:21]
	v_mfma_f32_16x16x32_bf16 v[14:17], v[198:201], v[182:185], v[14:17]
	v_mfma_f32_16x16x32_bf16 v[10:13], v[198:201], v[190:193], v[10:13]
	v_mfma_f32_16x16x32_bf16 v[6:9], v[240:243], v[182:185], v[6:9]
	v_mfma_f32_16x16x32_bf16 v[2:5], v[240:243], v[190:193], v[2:5]
	v_mfma_f32_16x16x32_bf16 v[118:121], v[78:81], v[186:189], v[30:33]
	v_mfma_f32_16x16x32_bf16 v[114:117], v[78:81], v[194:197], v[26:29]
	v_mfma_f32_16x16x32_bf16 v[102:105], v[94:97], v[186:189], v[22:25]
	v_mfma_f32_16x16x32_bf16 v[98:101], v[94:97], v[194:197], v[18:21]
	v_mfma_f32_16x16x32_bf16 v[86:89], v[202:205], v[186:189], v[14:17]
	v_mfma_f32_16x16x32_bf16 v[82:85], v[202:205], v[194:197], v[10:13]
	v_mfma_f32_16x16x32_bf16 v[70:73], v[244:247], v[186:189], v[6:9]
	v_mfma_f32_16x16x32_bf16 v[66:69], v[244:247], v[194:197], v[2:5]
	s_setprio 0
	s_barrier
	ds_read_b128 v[10:13], v137 offset:49152
	ds_read_b128 v[14:17], v137 offset:50176
	ds_read_b128 v[248:251], v137 offset:51200
	ds_read_b128 v[138:141], v137 offset:52224
	s_waitcnt vmcnt(0)
	s_barrier
	s_waitcnt lgkmcnt(0)
	s_setprio 3
	s_waitcnt lgkmcnt(0)
	v_mfma_f32_16x16x32_bf16 v[2:5], v[74:77], v[10:13], v[62:65]
	v_mfma_f32_16x16x32_bf16 v[126:129], v[78:81], v[14:17], v[2:5]
	v_mfma_f32_16x16x32_bf16 v[2:5], v[74:77], v[248:251], v[58:61]
	v_mfma_f32_16x16x32_bf16 v[122:125], v[78:81], v[138:141], v[2:5]
	v_mfma_f32_16x16x32_bf16 v[2:5], v[90:93], v[10:13], v[54:57]
	v_mfma_f32_16x16x32_bf16 v[110:113], v[94:97], v[14:17], v[2:5]
	v_mfma_f32_16x16x32_bf16 v[2:5], v[90:93], v[248:251], v[50:53]
	v_mfma_f32_16x16x32_bf16 v[106:109], v[94:97], v[138:141], v[2:5]
	v_mfma_f32_16x16x32_bf16 v[2:5], v[198:201], v[10:13], v[46:49]
	v_mfma_f32_16x16x32_bf16 v[94:97], v[202:205], v[14:17], v[2:5]
	v_mfma_f32_16x16x32_bf16 v[2:5], v[198:201], v[248:251], v[42:45]
	v_mfma_f32_16x16x32_bf16 v[90:93], v[202:205], v[138:141], v[2:5]
	v_mfma_f32_16x16x32_bf16 v[2:5], v[240:243], v[10:13], v[38:41]
	v_mfma_f32_16x16x32_bf16 v[78:81], v[244:247], v[14:17], v[2:5]
	v_mfma_f32_16x16x32_bf16 v[2:5], v[240:243], v[248:251], v[34:37]
	v_mfma_f32_16x16x32_bf16 v[74:77], v[244:247], v[138:141], v[2:5]
	s_setprio 0
	s_barrier
	ds_read_b128 v[26:29], v136 offset:49152
	ds_read_b128 v[30:33], v136 offset:50176
	ds_read_b128 v[42:45], v136 offset:51200
	ds_read_b128 v[198:201], v136 offset:52224
	ds_read_b128 v[202:205], v136 offset:53248
	ds_read_b128 v[240:243], v136 offset:54272
	ds_read_b128 v[244:247], v136 offset:55296
	ds_read_b128 v[212:215], v136 offset:56320
	s_barrier
	s_waitcnt lgkmcnt(0)
	s_setprio 3
	s_waitcnt lgkmcnt(0)
	v_mfma_f32_16x16x32_bf16 v[2:5], v[26:29], v[182:185], v[216:219]
	v_mfma_f32_16x16x32_bf16 v[54:57], v[30:33], v[186:189], v[2:5]
	v_mfma_f32_16x16x32_bf16 v[2:5], v[26:29], v[190:193], v[220:223]
	v_mfma_f32_16x16x32_bf16 v[50:53], v[30:33], v[194:197], v[2:5]
	v_mfma_f32_16x16x32_bf16 v[2:5], v[42:45], v[182:185], v[224:227]
	v_mfma_f32_16x16x32_bf16 v[38:41], v[198:201], v[186:189], v[2:5]
	v_mfma_f32_16x16x32_bf16 v[2:5], v[42:45], v[190:193], v[228:231]
	v_mfma_f32_16x16x32_bf16 v[34:37], v[198:201], v[194:197], v[2:5]
	v_mfma_f32_16x16x32_bf16 v[2:5], v[202:205], v[182:185], v[232:235]
	v_mfma_f32_16x16x32_bf16 v[22:25], v[240:243], v[186:189], v[2:5]
	v_mfma_f32_16x16x32_bf16 v[2:5], v[202:205], v[190:193], v[236:239]
	v_mfma_f32_16x16x32_bf16 v[18:21], v[240:243], v[194:197], v[2:5]
	v_mfma_f32_16x16x32_bf16 v[2:5], v[244:247], v[182:185], v[142:145]
	v_mfma_f32_16x16x32_bf16 v[6:9], v[212:215], v[186:189], v[2:5]
	v_mfma_f32_16x16x32_bf16 v[2:5], v[244:247], v[190:193], v[146:149]
	v_mfma_f32_16x16x32_bf16 v[2:5], v[212:215], v[194:197], v[2:5]
	s_setprio 0
	s_setprio 3
	v_mfma_f32_16x16x32_bf16 v[46:49], v[26:29], v[10:13], v[150:153]
	v_mfma_f32_16x16x32_bf16 v[26:29], v[26:29], v[248:251], v[154:157]
	v_mfma_f32_16x16x32_bf16 v[58:61], v[30:33], v[138:141], v[26:29]
	v_mfma_f32_16x16x32_bf16 v[26:29], v[42:45], v[10:13], v[158:161]
	v_mfma_f32_16x16x32_bf16 v[62:65], v[30:33], v[14:17], v[46:49]
	v_mfma_f32_16x16x32_bf16 v[46:49], v[198:201], v[14:17], v[26:29]
	v_mfma_f32_16x16x32_bf16 v[26:29], v[42:45], v[248:251], v[162:165]
	v_mfma_f32_16x16x32_bf16 v[42:45], v[198:201], v[138:141], v[26:29]
	v_mfma_f32_16x16x32_bf16 v[26:29], v[202:205], v[10:13], v[166:169]
	v_mfma_f32_16x16x32_bf16 v[10:13], v[244:247], v[10:13], v[174:177]
	v_mfma_f32_16x16x32_bf16 v[30:33], v[240:243], v[14:17], v[26:29]
	v_mfma_f32_16x16x32_bf16 v[26:29], v[202:205], v[248:251], v[170:173]
	v_mfma_f32_16x16x32_bf16 v[14:17], v[212:215], v[14:17], v[10:13]
	v_mfma_f32_16x16x32_bf16 v[10:13], v[244:247], v[248:251], v[178:181]
	v_mfma_f32_16x16x32_bf16 v[26:29], v[240:243], v[138:141], v[26:29]
	v_mfma_f32_16x16x32_bf16 v[10:13], v[212:215], v[138:141], v[10:13]
	s_setprio 0
	s_and_b64 vcc, exec, s[10:11]
	s_barrier
	s_cbranch_vccz .LBB0_471
	s_barrier
